# LRU tile loop software-pipelined: next tile's conv weight + input-row loads issued before the end-of-tile barrier/copy-out; tile start waits vmcnt(8) only
# speedup vs baseline: 1.0055x; 1.0020x over previous
; DI unsigned cvtpk(float lo, float hi) { unsigned r; asm volatile("v_cvt_pk_bf16_f32 %0, %1, %2" : "=v"(r) : "v"(lo), "v"(hi)); return r; }
; DI void lru_tile(const Params& p, unsigned char* shm, int c, int nb, const LruPar par) {
;     ...
;             if (qq == q) { carry[rt] = cin; pref[rt] = pa; }
;             cin = fmaf(ah[0], cin, ah[1]); pa *= ah[0];
;         }
;         if (q == 0) AGG[((size_t)d * 128 + c) * 2048 + chg] = (f32x2){pa, cin};
; #pragma unroll
;         for (int rt = 0; rt < 8; ++rt) {
;             const f32x2 cr2 = {carry[rt], carry[rt]}, pf2 = {pref[rt] * 255.f, pref[rt] * 255.f}, half2 = {0.5f, 0.5f};
; #pragma unroll
;             for (int jp = 0; jp < 2; ++jp) {
;                 const f32x2 pc2 = {pc[rt][2 * jp], pc[rt][2 * jp + 1]}, hl2 = {hl[rt][2 * jp], hl[rt][2 * jp + 1]};
;                 const f32x2 hf = pc2 * cr2 + hl2, pq = pc2 * pf2 + half2;
;                 const unsigned q0 = (unsigned)pq[0], q1 = (unsigned)pq[1];
;                 if (d == 0) { hsum[rt][2 * jp] = hf[0]; hsum[rt][2 * jp + 1] = hf[1]; ppk[rt][jp] = q0 | (q1 << 16); }
;                 else {
;                     const int lo = (rt * 16 + 4 * q + 2 * jp) * LDU + chl;
;                     const unsigned w = cvtpk(hsum[rt][2 * jp] + hf[0], hsum[rt][2 * jp + 1] + hf[1]);
;                     OS[lo] = (unsigned short)(w & 0xffffu); OS[lo + LDU] = (unsigned short)(w >> 16);
;                     const unsigned pw = ppk[rt][jp] | (q0 << 8) | (q1 << 24);
;                     PS[lo] = (unsigned short)(pw & 0xffffu); PS[lo + LDU] = (unsigned short)(pw >> 16);
;                 }
; DI void phase_lru(const Params& p, unsigned char* shm) {
;     int nbp = -1; LruPar par;
;     for (int it = blockIdx.x; it < 2048; it += gridDim.x) { const int nb = it & 15; if (nb != nbp) { par = lru_params(p, nb); nbp = nb; } lru_tile(p, shm, it >> 4, nb, par); }
.LBB0_207:
	s_waitcnt lgkmcnt(0)
	s_cmp_lt_i32 s4, 3
	s_cselect_b64 s[6:7], -1, 0
	s_cmp_gt_i32 s5, 2
	s_cselect_b64 s[4:5], -1, 0
	s_and_b64 s[4:5], s[6:7], s[4:5]
	s_andn2_b64 vcc, exec, s[4:5]
	s_cbranch_vccnz .LBB0_266
	s_load_dword s4, s[0:1], 0xd0
	s_waitcnt lgkmcnt(0)
	s_bitcmp0_b32 s4, 0
	s_cbranch_scc1 .LBB0_234
	s_cmpk_gt_i32 s2, 0x7ff
	s_cbranch_scc1 .LBB0_233
	s_load_dwordx4 s[12:15], s[0:1], 0x40
	s_load_dwordx4 s[16:19], s[0:1], 0x78
	s_load_dwordx4 s[20:23], s[0:1], 0x18
	s_load_dwordx2 s[30:31], s[0:1], 0x30
	s_waitcnt vmcnt(0)
	v_lshrrev_b32_e32 v0, 2, v202
	v_and_b32_e32 v1, 15, v202
	s_movk_i32 s4, 0xf0
	s_waitcnt lgkmcnt(0)
	s_add_u32 s37, s18, 0x1ba00000
	s_addc_u32 s41, s19, 0
	s_add_u32 s34, s18, 0x1c000000
	s_addc_u32 s35, s19, 0
	s_add_u32 s43, s16, 0x4000000
	v_mov_b32_e32 v69, 0
	v_and_or_b32 v71, v0, s4, v1
	s_addc_u32 s45, s17, 0
	s_mov_b32 s70, -1
	s_mov_b32 s36, 0xbfb8aa3b
	s_mov_b32 s47, 0x42ce8ed0
	s_mov_b32 s39, 0
	s_mov_b32 s49, 0xc2b17218
	s_mov_b32 s51, 0x7f800000
	s_movk_i32 s62, 0x2000
	s_mov_b32 s63, 0x3f2aaaab
	s_mov_b32 s40, 0x3e9b6dac
	s_mov_b32 s42, 0x3f2aaada
	s_mov_b32 s44, 0x3f317218
	s_mov_b32 s46, 0xb102e308
	s_mov_b32 s64, 0x33800000
	s_mov_b32 s48, 0xc1000000
	s_mov_b32 s50, 0x3fb8aa3b
	s_mov_b64 s[52:53], 0x2000
	s_mov_b64 s[54:55], 0x4000
	s_movk_i32 s65, 0x4000
	s_mov_b64 s[56:57], 0x6000
	s_movk_i32 s66, 0x6000
	s_movk_i32 s67, 0x110
	s_add_i32 s68, 0, 0x11000
	v_mov_b32_e32 v73, 0x7f800000
	v_mov_b32_e32 v70, 0x3ecc95a3
	s_mov_b32 s69, s2
	v_mov_b32_e32 v180, 0
	v_mov_b32_e32 v162, 0
	v_mov_b32_e32 v91, 0
	v_mov_b32_e32 v89, 0
	v_mov_b32_e32 v85, 0
	v_mov_b32_e32 v81, 0
	v_mov_b32_e32 v79, 0
	v_mov_b32_e32 v77, 0
	v_mov_b32_e32 v90, v69
	v_mov_b32_e32 v88, v69
	v_mov_b32_e32 v84, v69
	v_mov_b32_e32 v80, v69
	v_mov_b32_e32 v78, v69
	v_mov_b32_e32 v76, v69
	v_mov_b32_e32 v74, v69
	v_mov_b32_e32 v72, v69
	s_mov_b32 s71, 0
	s_branch .LBB0_212
.LBB0_211:
	s_or_b64 exec, exec, s[60:61]
	v_cndmask_b32_e64 v56, v90, 0, s[10:11]
	v_cndmask_b32_e64 v56, v56, v119, s[4:5]
	v_cndmask_b32_e64 v56, v56, v127, s[6:7]
	v_cndmask_b32_e64 v178, v56, v129, s[8:9]
	v_cndmask_b32_e64 v56, v88, v137, s[10:11]
	v_cndmask_b32_e64 v56, v56, v139, s[4:5]
	v_cndmask_b32_e64 v56, v56, v147, s[6:7]
	v_cndmask_b32_e64 v238, v56, v149, s[8:9]
	v_cndmask_b32_e64 v56, v84, v157, s[10:11]
	v_cndmask_b32_e64 v56, v56, v159, s[4:5]
	v_cndmask_b32_e64 v56, v56, v183, s[6:7]
	v_cndmask_b32_e64 v184, v56, v184, s[8:9]
	v_cndmask_b32_e64 v56, v80, v185, s[10:11]
	v_cndmask_b32_e64 v56, v56, v186, s[4:5]
	v_cndmask_b32_e64 v56, v56, v187, s[6:7]
	v_cndmask_b32_e64 v186, v56, v188, s[8:9]
	v_cndmask_b32_e64 v56, v78, v189, s[10:11]
	v_cndmask_b32_e64 v56, v56, v190, s[4:5]
	v_cndmask_b32_e64 v56, v56, v192, s[6:7]
	v_cndmask_b32_e64 v188, v56, v193, s[8:9]
	v_cndmask_b32_e64 v56, v76, v194, s[10:11]
	v_cndmask_b32_e64 v56, v56, v195, s[4:5]
	v_cndmask_b32_e64 v56, v56, v196, s[6:7]
	v_cndmask_b32_e64 v190, v56, v197, s[8:9]
	v_cndmask_b32_e64 v56, v74, v198, s[10:11]
	v_cndmask_b32_e64 v56, v56, v200, s[4:5]
	v_cndmask_b32_e64 v56, v56, v201, s[6:7]
	v_cndmask_b32_e64 v192, v56, v204, s[8:9]
	v_cndmask_b32_e64 v56, v72, v205, s[10:11]
	v_cndmask_b32_e64 v56, v56, v206, s[4:5]
	v_cndmask_b32_e64 v56, v56, v207, s[6:7]
	v_cndmask_b32_e64 v194, v56, v163, s[8:9]
	v_cndmask_b32_e64 v56, v56, 0, s[8:9]
	v_mul_f32_e32 v196, 0x437f0000, v199
	v_mov_b32_e32 v159, v154
	v_cndmask_b32_e64 v7, v56, v7, s[6:7]
	v_pk_fma_f32 v[56:57], v[158:159], v[196:197], 0.5 op_sel_hi:[1,0,0]
	v_mov_b32_e32 v157, v155
	v_pk_fma_f32 v[154:155], v[150:151], v[196:197], 0.5 op_sel_hi:[1,0,0]
	v_pk_fma_f32 v[150:151], v[150:151], v[194:195], v[152:153] op_sel_hi:[1,0,1]
	v_mul_f32_e32 v152, 0x437f0000, v191
	v_mov_b32_e32 v149, v144
	v_cvt_u32_f32_sdwa v163, v57 dst_sel:WORD_1 dst_unused:UNUSED_PAD src0_sel:DWORD
	v_cvt_u32_f32_e32 v179, v56
	v_pk_fma_f32 v[56:57], v[158:159], v[194:195], v[156:157] op_sel_hi:[1,0,1]
	v_cvt_u32_f32_sdwa v156, v155 dst_sel:WORD_1 dst_unused:UNUSED_PAD src0_sel:DWORD
	v_cvt_u32_f32_e32 v157, v154
	v_pk_fma_f32 v[154:155], v[148:149], v[152:153], 0.5 op_sel_hi:[1,0,0]
	v_mov_b32_e32 v147, v145
	v_cvt_u32_f32_e32 v153, v154
	v_pk_fma_f32 v[144:145], v[148:149], v[192:193], v[146:147] op_sel_hi:[1,0,1]
	v_mov_b32_e32 v139, v134
	v_mov_b32_e32 v137, v135
	v_pk_fma_f32 v[146:147], v[140:141], v[152:153], 0.5 op_sel_hi:[1,0,0]
	v_pk_fma_f32 v[140:141], v[140:141], v[192:193], v[142:143] op_sel_hi:[1,0,1]
	v_mul_f32_e32 v142, 0x437f0000, v182
	v_cvt_u32_f32_sdwa v148, v147 dst_sel:WORD_1 dst_unused:UNUSED_PAD src0_sel:DWORD
	v_cvt_u32_f32_e32 v149, v146
	v_pk_fma_f32 v[146:147], v[138:139], v[142:143], 0.5 op_sel_hi:[1,0,0]
	v_pk_fma_f32 v[134:135], v[138:139], v[190:191], v[136:137] op_sel_hi:[1,0,1]
	v_cvt_u32_f32_e32 v143, v146
	v_mov_b32_e32 v129, v124
	v_mov_b32_e32 v127, v125
	v_pk_fma_f32 v[124:125], v[128:129], v[188:189], v[126:127] op_sel_hi:[1,0,1]
	v_pk_fma_f32 v[136:137], v[130:131], v[142:143], 0.5 op_sel_hi:[1,0,0]
	v_pk_fma_f32 v[130:131], v[130:131], v[190:191], v[132:133] op_sel_hi:[1,0,1]
	v_mul_f32_e32 v132, 0x437f0000, v117
	v_cvt_u32_f32_sdwa v138, v137 dst_sel:WORD_1 dst_unused:UNUSED_PAD src0_sel:DWORD
	v_cvt_u32_f32_e32 v139, v136
	v_pk_fma_f32 v[136:137], v[128:129], v[132:133], 0.5 op_sel_hi:[1,0,0]
	v_mov_b32_e32 v119, v114
	v_cvt_u32_f32_e32 v133, v136
	v_mov_b32_e32 v117, v115
	v_cndmask_b32_e64 v7, v7, v15, s[4:5]
	v_pk_fma_f32 v[114:115], v[118:119], v[186:187], v[116:117] op_sel_hi:[1,0,1]
	v_pk_fma_f32 v[126:127], v[120:121], v[132:133], 0.5 op_sel_hi:[1,0,0]
; DI unsigned cvtpk(float lo, float hi) { unsigned r; asm volatile("v_cvt_pk_bf16_f32 %0, %1, %2" : "=v"(r) : "v"(lo), "v"(hi)); return r; }
; DI void lru_tile(const Params& p, unsigned char* shm, int c, int nb, const LruPar par) {
;     ...
;         for (int rt = 0; rt < 8; ++rt) {
;             const f32x2 cr2 = {carry[rt], carry[rt]}, pf2 = {pref[rt] * 255.f, pref[rt] * 255.f}, half2 = {0.5f, 0.5f};
; #pragma unroll
;             for (int jp = 0; jp < 2; ++jp) {
;                 const f32x2 pc2 = {pc[rt][2 * jp], pc[rt][2 * jp + 1]}, hl2 = {hl[rt][2 * jp], hl[rt][2 * jp + 1]};
;                 const f32x2 hf = pc2 * cr2 + hl2, pq = pc2 * pf2 + half2;
;                 const unsigned q0 = (unsigned)pq[0], q1 = (unsigned)pq[1];
;                 if (d == 0) { hsum[rt][2 * jp] = hf[0]; hsum[rt][2 * jp + 1] = hf[1]; ppk[rt][jp] = q0 | (q1 << 16); }
;                 else {
;                     const int lo = (rt * 16 + 4 * q + 2 * jp) * LDU + chl;
;                     const unsigned w = cvtpk(hsum[rt][2 * jp] + hf[0], hsum[rt][2 * jp + 1] + hf[1]);
;                     OS[lo] = (unsigned short)(w & 0xffffu); OS[lo + LDU] = (unsigned short)(w >> 16);
;                     const unsigned pw = ppk[rt][jp] | (q0 << 8) | (q1 << 24);
;                     PS[lo] = (unsigned short)(pw & 0xffffu); PS[lo + LDU] = (unsigned short)(pw >> 16);
;                 }
	v_pk_fma_f32 v[120:121], v[120:121], v[188:189], v[122:123] op_sel_hi:[1,0,1]
	v_mul_f32_e32 v122, 0x437f0000, v109
	v_cvt_u32_f32_sdwa v128, v127 dst_sel:WORD_1 dst_unused:UNUSED_PAD src0_sel:DWORD
	v_cvt_u32_f32_e32 v129, v126
	v_pk_fma_f32 v[126:127], v[118:119], v[122:123], 0.5 op_sel_hi:[1,0,0]
	v_mov_b32_e32 v109, v104
	v_cvt_u32_f32_sdwa v123, v127 dst_sel:WORD_1 dst_unused:UNUSED_PAD src0_sel:DWORD
	v_cndmask_b32_e64 v72, v7, v23, s[10:11]
	v_cndmask_b32_e64 v7, v192, v39, s[8:9]
	v_cndmask_b32_e64 v7, v7, v47, s[6:7]
	v_pk_fma_f32 v[116:117], v[110:111], v[122:123], 0.5 op_sel_hi:[1,0,0]
	v_pk_fma_f32 v[110:111], v[110:111], v[186:187], v[112:113] op_sel_hi:[1,0,1]
	v_mul_f32_e32 v112, 0x437f0000, v107
	v_cvt_u32_f32_sdwa v118, v117 dst_sel:WORD_1 dst_unused:UNUSED_PAD src0_sel:DWORD
	v_cvt_u32_f32_e32 v119, v116
	v_pk_fma_f32 v[116:117], v[108:109], v[112:113], 0.5 op_sel_hi:[1,0,0]
	v_cndmask_b32_e64 v7, v7, v61, s[4:5]
	v_cvt_u32_f32_e32 v113, v116
	v_cndmask_b32_e64 v74, v7, v97, s[10:11]
	v_cndmask_b32_e64 v7, v190, v171, s[8:9]
	v_cndmask_b32_e64 v7, v7, v177, s[6:7]
	v_mov_b32_e32 v107, v105
	v_cndmask_b32_e64 v7, v7, v215, s[4:5]
	v_pk_fma_f32 v[104:105], v[108:109], v[184:185], v[106:107] op_sel_hi:[1,0,1]
	v_pk_fma_f32 v[106:107], v[100:101], v[112:113], 0.5 op_sel_hi:[1,0,0]
	v_pk_fma_f32 v[100:101], v[100:101], v[184:185], v[102:103] op_sel_hi:[1,0,1]
	v_mul_f32_e32 v102, 0x437f0000, v99
	v_mov_b32_e32 v99, v66
	v_cndmask_b32_e64 v76, v7, v216, s[10:11]
	v_cndmask_b32_e64 v7, v188, v217, s[8:9]
	v_cvt_u32_f32_sdwa v108, v107 dst_sel:WORD_1 dst_unused:UNUSED_PAD src0_sel:DWORD
	v_cvt_u32_f32_e32 v109, v106
	v_pk_fma_f32 v[106:107], v[98:99], v[102:103], 0.5 op_sel_hi:[1,0,0]
	v_cndmask_b32_e64 v7, v7, v218, s[6:7]
	v_cvt_u32_f32_e32 v103, v106
	v_cndmask_b32_e64 v7, v7, v219, s[4:5]
	v_cndmask_b32_e64 v78, v7, v220, s[10:11]
	v_cndmask_b32_e64 v7, v186, v221, s[8:9]
	v_cndmask_b32_e64 v7, v7, v222, s[6:7]
	v_mov_b32_e32 v97, v67
	v_cndmask_b32_e64 v7, v7, v223, s[4:5]
	v_pk_fma_f32 v[66:67], v[98:99], v[238:239], v[96:97] op_sel_hi:[1,0,1]
	v_pk_fma_f32 v[96:97], v[62:63], v[102:103], 0.5 op_sel_hi:[1,0,0]
	v_pk_fma_f32 v[62:63], v[62:63], v[238:239], v[64:65] op_sel_hi:[1,0,1]
	v_mul_f32_e32 v64, 0x437f0000, v181
	v_mov_b32_e32 v61, v54
	v_cndmask_b32_e64 v80, v7, v224, s[10:11]
	v_cndmask_b32_e64 v7, v184, v225, s[8:9]
	v_cvt_u32_f32_sdwa v98, v97 dst_sel:WORD_1 dst_unused:UNUSED_PAD src0_sel:DWORD
	v_cvt_u32_f32_e32 v99, v96
	v_pk_fma_f32 v[96:97], v[60:61], v[64:65], 0.5 op_sel_hi:[1,0,0]
	v_cndmask_b32_e64 v7, v7, v226, s[6:7]
	v_cvt_u32_f32_sdwa v65, v97 dst_sel:WORD_1 dst_unused:UNUSED_PAD src0_sel:DWORD
	v_cndmask_b32_e64 v7, v7, v227, s[4:5]
	v_cndmask_b32_e64 v84, v7, v228, s[10:11]
	v_cndmask_b32_e64 v7, v238, v229, s[8:9]
	v_cndmask_b32_e64 v7, v7, v230, s[6:7]
	v_mov_b32_e32 v59, v55
	v_cndmask_b32_e64 v7, v7, v231, s[4:5]
	v_pk_fma_f32 v[54:55], v[60:61], v[178:179], v[58:59] op_sel_hi:[1,0,1]
	v_pk_fma_f32 v[58:59], v[50:51], v[64:65], 0.5 op_sel_hi:[1,0,0]
	v_pk_fma_f32 v[50:51], v[50:51], v[178:179], v[52:53] op_sel_hi:[1,0,1]
	v_mul_f32_e32 v52, 0x437f0000, v31
	v_mov_b32_e32 v171, v49
	v_cndmask_b32_e64 v88, v7, v232, s[10:11]
	v_cndmask_b32_e64 v7, v178, v233, s[8:9]
	v_cvt_u32_f32_sdwa v60, v59 dst_sel:WORD_1 dst_unused:UNUSED_PAD src0_sel:DWORD
	v_cvt_u32_f32_e32 v61, v58
	v_pk_fma_f32 v[58:59], v[170:171], v[52:53], 0.5 op_sel_hi:[1,0,0]
	v_cndmask_b32_e64 v7, v7, v234, s[6:7]
	v_cvt_u32_f32_e32 v49, v58
	v_cndmask_b32_e64 v7, v7, v235, s[4:5]
	v_cndmask_b32_e64 v90, v7, v236, s[10:11]
	v_cvt_u32_f32_e32 v31, v59
	v_pk_fma_f32 v[58:59], v[170:171], v[90:91], v[168:169] op_sel_hi:[1,0,1]
	v_add_lshl_u32 v53, v48, v95, 1
	v_pk_add_f32 v[50:51], v[50:51], v[58:59]
	v_lshlrev_b32_e32 v48, 8, v49
	v_cvt_pk_bf16_f32 v50, v50, v51
	v_add_u32_e32 v58, s68, v53
	v_or3_b32 v48, v60, v61, v48
	ds_write_b16 v58, v50
	ds_write_b16_d16_hi v58, v50 offset:272
	v_lshl_or_b32 v31, v31, 24, v48
	ds_write_b16 v68, v48 offset:34816
	ds_write_b16_d16_hi v68, v31 offset:35088
	v_pk_fma_f32 v[48:49], v[160:161], v[52:53], 0.5 op_sel_hi:[1,0,0]
	v_cvt_u32_f32_e32 v96, v96
	v_cvt_u32_f32_e32 v50, v48
	v_cvt_u32_f32_e32 v31, v49
	v_pk_fma_f32 v[48:49], v[160:161], v[90:91], v[166:167] op_sel_hi:[1,0,1]
	v_cvt_u32_f32_sdwa v7, v155 dst_sel:WORD_1 dst_unused:UNUSED_PAD src0_sel:DWORD
	v_pk_add_f32 v[48:49], v[54:55], v[48:49]
	v_cvt_u32_f32_sdwa v15, v147 dst_sel:WORD_1 dst_unused:UNUSED_PAD src0_sel:DWORD
	v_cvt_pk_bf16_f32 v48, v48, v49
	ds_write_b16 v58, v48 offset:544
	ds_write_b16_d16_hi v58, v48 offset:816
	v_lshlrev_b32_e32 v48, 8, v50
	v_or3_b32 v48, v65, v96, v48
	v_cvt_u32_f32_sdwa v23, v137 dst_sel:WORD_1 dst_unused:UNUSED_PAD src0_sel:DWORD
	v_cvt_u32_f32_e32 v126, v126
	v_cvt_u32_f32_sdwa v39, v117 dst_sel:WORD_1 dst_unused:UNUSED_PAD src0_sel:DWORD
	v_cvt_u32_f32_sdwa v47, v107 dst_sel:WORD_1 dst_unused:UNUSED_PAD src0_sel:DWORD
	v_lshl_or_b32 v31, v31, 24, v48
	ds_write_b16 v68, v48 offset:35360
	ds_write_b16_d16_hi v68, v31 offset:35632
	v_mul_f32_e32 v48, 0x437f0000, v162
	v_mov_b32_e32 v177, v208
	v_pk_fma_f32 v[50:51], v[176:177], v[48:49], 0.5 op_sel_hi:[1,0,0]
	s_nop 0
	v_cvt_u32_f32_e32 v49, v50
	v_cvt_u32_f32_e32 v31, v51
	v_pk_fma_f32 v[50:51], v[176:177], v[88:89], v[174:175] op_sel_hi:[1,0,1]
	v_lshlrev_b32_e32 v49, 8, v49
	v_pk_add_f32 v[50:51], v[62:63], v[50:51]
	v_or3_b32 v49, v98, v99, v49
	v_cvt_pk_bf16_f32 v50, v50, v51
	ds_write_b16 v58, v50 offset:4352
	ds_write_b16_d16_hi v58, v50 offset:4624
	v_lshl_or_b32 v31, v31, 24, v49
	ds_write_b16 v68, v49 offset:39168
	ds_write_b16_d16_hi v68, v31 offset:39440
; DI unsigned cvtpk(float lo, float hi) { unsigned r; asm volatile("v_cvt_pk_bf16_f32 %0, %1, %2" : "=v"(r) : "v"(lo), "v"(hi)); return r; }
; DI void lru_tile(const Params& p, unsigned char* shm, int c, int nb, const LruPar par) {
;     ...
;         for (int rt = 0; rt < 8; ++rt) {
;             const f32x2 cr2 = {carry[rt], carry[rt]}, pf2 = {pref[rt] * 255.f, pref[rt] * 255.f}, half2 = {0.5f, 0.5f};
; #pragma unroll
;             for (int jp = 0; jp < 2; ++jp) {
;                 const f32x2 pc2 = {pc[rt][2 * jp], pc[rt][2 * jp + 1]}, hl2 = {hl[rt][2 * jp], hl[rt][2 * jp + 1]};
;                 const f32x2 hf = pc2 * cr2 + hl2, pq = pc2 * pf2 + half2;
;                 const unsigned q0 = (unsigned)pq[0], q1 = (unsigned)pq[1];
;                 if (d == 0) { hsum[rt][2 * jp] = hf[0]; hsum[rt][2 * jp + 1] = hf[1]; ppk[rt][jp] = q0 | (q1 << 16); }
;                 else {
;                     const int lo = (rt * 16 + 4 * q + 2 * jp) * LDU + chl;
;                     const unsigned w = cvtpk(hsum[rt][2 * jp] + hf[0], hsum[rt][2 * jp + 1] + hf[1]);
;                     OS[lo] = (unsigned short)(w & 0xffffu); OS[lo + LDU] = (unsigned short)(w >> 16);
;                     const unsigned pw = ppk[rt][jp] | (q0 << 8) | (q1 << 24);
;                     PS[lo] = (unsigned short)(pw & 0xffffu); PS[lo + LDU] = (unsigned short)(pw >> 16);
;                 }
	v_pk_fma_f32 v[48:49], v[164:165], v[48:49], 0.5 op_sel_hi:[1,0,0]
	s_nop 0
	v_cvt_u32_f32_e32 v50, v48
	v_cvt_u32_f32_e32 v31, v49
	v_pk_fma_f32 v[48:49], v[164:165], v[88:89], v[172:173] op_sel_hi:[1,0,1]
	s_nop 0
	v_pk_add_f32 v[48:49], v[66:67], v[48:49]
	s_nop 0
	v_cvt_pk_bf16_f32 v48, v48, v49
	ds_write_b16 v58, v48 offset:4896
	ds_write_b16_d16_hi v58, v48 offset:5168
	v_lshlrev_b32_e32 v48, 8, v50
	v_or3_b32 v47, v47, v103, v48
	v_lshl_or_b32 v31, v31, 24, v47
	ds_write_b16 v68, v47 offset:39712
	ds_write_b16_d16_hi v68, v31 offset:39984
	v_mul_f32_e32 v48, 0x437f0000, v91
	v_mov_b32_e32 v47, v209
	v_pk_fma_f32 v[50:51], v[46:47], v[48:49], 0.5 op_sel_hi:[1,0,0]
	v_pk_fma_f32 v[44:45], v[46:47], v[84:85], v[44:45] op_sel_hi:[1,0,1]
	v_cvt_u32_f32_e32 v49, v50
	v_cvt_u32_f32_e32 v31, v51
	v_pk_add_f32 v[44:45], v[100:101], v[44:45]
	v_pk_fma_f32 v[40:41], v[42:43], v[84:85], v[40:41] op_sel_hi:[1,0,1]
	v_cvt_pk_bf16_f32 v44, v44, v45
	ds_write_b16 v58, v44 offset:8704
	ds_write_b16_d16_hi v58, v44 offset:8976
	v_lshlrev_b32_e32 v44, 8, v49
	v_or3_b32 v44, v108, v109, v44
	v_lshl_or_b32 v31, v31, 24, v44
	ds_write_b16 v68, v44 offset:43520
	ds_write_b16_d16_hi v68, v31 offset:43792
	v_pk_fma_f32 v[44:45], v[42:43], v[48:49], 0.5 op_sel_hi:[1,0,0]
	v_pk_add_f32 v[40:41], v[104:105], v[40:41]
	v_cvt_u32_f32_e32 v44, v44
	v_cvt_u32_f32_e32 v31, v45
	v_cvt_pk_bf16_f32 v40, v40, v41
	ds_write_b16 v58, v40 offset:9248
	ds_write_b16_d16_hi v58, v40 offset:9520
	v_lshlrev_b32_e32 v40, 8, v44
	v_or3_b32 v39, v39, v113, v40
	v_lshl_or_b32 v31, v31, 24, v39
	ds_write_b16 v68, v39 offset:44064
	ds_write_b16_d16_hi v68, v31 offset:44336
	v_mul_f32_e32 v40, 0x437f0000, v89
	v_mov_b32_e32 v39, v210
	v_pk_fma_f32 v[42:43], v[38:39], v[40:41], 0.5 op_sel_hi:[1,0,0]
	v_pk_fma_f32 v[36:37], v[38:39], v[80:81], v[36:37] op_sel_hi:[1,0,1]
	v_cvt_u32_f32_e32 v41, v42
	v_cvt_u32_f32_e32 v31, v43
	v_pk_add_f32 v[36:37], v[110:111], v[36:37]
	v_pk_fma_f32 v[32:33], v[34:35], v[80:81], v[32:33] op_sel_hi:[1,0,1]
	v_cvt_pk_bf16_f32 v36, v36, v37
	ds_write_b16 v58, v36 offset:13056
	ds_write_b16_d16_hi v58, v36 offset:13328
	v_lshlrev_b32_e32 v36, 8, v41
	v_or3_b32 v36, v118, v119, v36
	v_lshl_or_b32 v31, v31, 24, v36
	ds_write_b16 v68, v36 offset:47872
	ds_write_b16_d16_hi v68, v31 offset:48144
	v_pk_fma_f32 v[36:37], v[34:35], v[40:41], 0.5 op_sel_hi:[1,0,0]
	v_pk_add_f32 v[32:33], v[114:115], v[32:33]
	v_cvt_u32_f32_e32 v36, v36
	v_cvt_u32_f32_e32 v31, v37
	v_cvt_pk_bf16_f32 v32, v32, v33
	ds_write_b16 v58, v32 offset:13600
	ds_write_b16_d16_hi v58, v32 offset:13872
	v_lshlrev_b32_e32 v32, 8, v36
	v_or3_b32 v32, v123, v126, v32
	v_lshl_or_b32 v31, v31, 24, v32
	ds_write_b16 v68, v32 offset:48416
	ds_write_b16_d16_hi v68, v31 offset:48688
	v_mul_f32_e32 v32, 0x437f0000, v85
	v_mov_b32_e32 v31, v211
	v_pk_fma_f32 v[34:35], v[30:31], v[32:33], 0.5 op_sel_hi:[1,0,0]
	v_pk_fma_f32 v[28:29], v[30:31], v[78:79], v[28:29] op_sel_hi:[1,0,1]
	v_cvt_u32_f32_e32 v34, v34
	v_cvt_u32_f32_e32 v33, v35
	v_pk_add_f32 v[28:29], v[120:121], v[28:29]
	v_pk_fma_f32 v[24:25], v[26:27], v[78:79], v[24:25] op_sel_hi:[1,0,1]
	v_cvt_pk_bf16_f32 v28, v28, v29
	ds_write_b16 v58, v28 offset:17408
	ds_write_b16_d16_hi v58, v28 offset:17680
	v_lshlrev_b32_e32 v28, 8, v34
	v_or3_b32 v28, v128, v129, v28
	v_lshl_or_b32 v29, v33, 24, v28
	ds_write_b16 v68, v28 offset:52224
	ds_write_b16_d16_hi v68, v29 offset:52496
	v_pk_fma_f32 v[28:29], v[26:27], v[32:33], 0.5 op_sel_hi:[1,0,0]
	v_pk_add_f32 v[24:25], v[124:125], v[24:25]
	v_cvt_u32_f32_e32 v28, v28
	v_cvt_u32_f32_e32 v29, v29
	v_cvt_pk_bf16_f32 v24, v24, v25
	ds_write_b16 v58, v24 offset:17952
	ds_write_b16_d16_hi v58, v24 offset:18224
	v_lshlrev_b32_e32 v24, 8, v28
	v_or3_b32 v23, v23, v133, v24
	v_lshl_or_b32 v24, v29, 24, v23
	ds_write_b16 v68, v23 offset:52768
	ds_write_b16_d16_hi v68, v24 offset:53040
	v_mul_f32_e32 v24, 0x437f0000, v81
	v_mov_b32_e32 v23, v212
	v_pk_fma_f32 v[26:27], v[22:23], v[24:25], 0.5 op_sel_hi:[1,0,0]
	v_pk_fma_f32 v[20:21], v[22:23], v[76:77], v[20:21] op_sel_hi:[1,0,1]
	v_cvt_u32_f32_e32 v26, v26
	v_cvt_u32_f32_e32 v25, v27
	v_pk_add_f32 v[20:21], v[130:131], v[20:21]
	v_pk_fma_f32 v[16:17], v[18:19], v[76:77], v[16:17] op_sel_hi:[1,0,1]
	v_cvt_pk_bf16_f32 v20, v20, v21
	ds_write_b16 v58, v20 offset:21760
	ds_write_b16_d16_hi v58, v20 offset:22032
	v_lshlrev_b32_e32 v20, 8, v26
	v_or3_b32 v20, v138, v139, v20
	v_lshl_or_b32 v21, v25, 24, v20
	ds_write_b16 v68, v20 offset:56576
	ds_write_b16_d16_hi v68, v21 offset:56848
	v_pk_fma_f32 v[20:21], v[18:19], v[24:25], 0.5 op_sel_hi:[1,0,0]
	v_pk_add_f32 v[16:17], v[134:135], v[16:17]
	v_cvt_u32_f32_e32 v20, v20
	v_cvt_u32_f32_e32 v21, v21
	v_cvt_pk_bf16_f32 v16, v16, v17
	ds_write_b16 v58, v16 offset:22304
	ds_write_b16_d16_hi v58, v16 offset:22576
	v_lshlrev_b32_e32 v16, 8, v20
	v_or3_b32 v15, v15, v143, v16
	v_lshl_or_b32 v16, v21, 24, v15
	ds_write_b16 v68, v15 offset:57120
	ds_write_b16_d16_hi v68, v16 offset:57392
	v_mul_f32_e32 v16, 0x437f0000, v79
	v_mov_b32_e32 v15, v213
	v_pk_fma_f32 v[18:19], v[14:15], v[16:17], 0.5 op_sel_hi:[1,0,0]
	v_pk_fma_f32 v[12:13], v[14:15], v[74:75], v[12:13] op_sel_hi:[1,0,1]
	v_cvt_u32_f32_e32 v18, v18
	v_cvt_u32_f32_e32 v17, v19
	v_pk_add_f32 v[12:13], v[140:141], v[12:13]
; DI unsigned cvtpk(float lo, float hi) { unsigned r; asm volatile("v_cvt_pk_bf16_f32 %0, %1, %2" : "=v"(r) : "v"(lo), "v"(hi)); return r; }
; DI float bflo(unsigned w) { return __uint_as_float(w << 16); }
; DI float bfhi(unsigned w) { return __uint_as_float(w & 0xffff0000u); }
; DI void lru_tile(const Params& p, unsigned char* shm, int c, int nb, const LruPar par) {
;     ...
;         for (int k = 0; k < 7; ++k) { const int t = c * 128 + rg * 4 - 2 + k;
;             u32x4 v = {0u, 0u, 0u, 0u};
;             if (t >= 0 && t < S) v = *(const u32x4*)(ZU + (size_t)(nb >> 1) * S * 256 + (size_t)t * 256 + (nb & 1) * 128 + cgp * 8);
; #pragma unroll
;             for (int i = 0; i < 4; ++i) { xr[k][2 * i] = bflo(v[i]); xr[k][2 * i + 1] = bfhi(v[i]); } }
;     ...
;                 if (d == 0) { hsum[rt][2 * jp] = hf[0]; hsum[rt][2 * jp + 1] = hf[1]; ppk[rt][jp] = q0 | (q1 << 16); }
;                 else {
;                     const int lo = (rt * 16 + 4 * q + 2 * jp) * LDU + chl;
;                     const unsigned w = cvtpk(hsum[rt][2 * jp] + hf[0], hsum[rt][2 * jp + 1] + hf[1]);
;                     OS[lo] = (unsigned short)(w & 0xffffu); OS[lo + LDU] = (unsigned short)(w >> 16);
;                     const unsigned pw = ppk[rt][jp] | (q0 << 8) | (q1 << 24);
;                     PS[lo] = (unsigned short)(pw & 0xffffu); PS[lo + LDU] = (unsigned short)(pw >> 16);
;                 }
;             }
;             __builtin_amdgcn_sched_barrier(0);
;         }
;     }
;     __syncthreads();
;     lru_copy_out(OS, (bf16_t*)((unsigned char*)p.out + DO_ACF) + (size_t)c * 128 * 2048 + nb * 128, tid);
;     lru_copy_out(PS, (bf16_t*)((unsigned char*)p.out + DO_ACB) + (size_t)c * 128 * 2048 + nb * 128, tid);
	v_pk_fma_f32 v[8:9], v[10:11], v[74:75], v[8:9] op_sel_hi:[1,0,1]
	v_cvt_pk_bf16_f32 v12, v12, v13
	ds_write_b16 v58, v12 offset:26112
	ds_write_b16_d16_hi v58, v12 offset:26384
	v_lshlrev_b32_e32 v12, 8, v18
	v_or3_b32 v12, v148, v149, v12
	v_lshl_or_b32 v13, v17, 24, v12
	ds_write_b16 v68, v12 offset:60928
	ds_write_b16_d16_hi v68, v13 offset:61200
	v_pk_fma_f32 v[12:13], v[10:11], v[16:17], 0.5 op_sel_hi:[1,0,0]
	v_pk_add_f32 v[8:9], v[144:145], v[8:9]
	v_cvt_u32_f32_e32 v12, v12
	v_cvt_u32_f32_e32 v13, v13
	v_cvt_pk_bf16_f32 v8, v8, v9
	ds_write_b16 v58, v8 offset:26656
	ds_write_b16_d16_hi v58, v8 offset:26928
	v_lshlrev_b32_e32 v8, 8, v12
	v_or3_b32 v7, v7, v153, v8
	v_lshl_or_b32 v8, v13, 24, v7
	ds_write_b16 v68, v7 offset:61472
	ds_write_b16_d16_hi v68, v8 offset:61744
	v_mul_f32_e32 v8, 0x437f0000, v77
	v_mov_b32_e32 v7, v214
	v_pk_fma_f32 v[10:11], v[6:7], v[8:9], 0.5 op_sel_hi:[1,0,0]
	v_pk_fma_f32 v[4:5], v[6:7], v[72:73], v[4:5] op_sel_hi:[1,0,1]
	v_cvt_u32_f32_e32 v10, v10
	v_cvt_u32_f32_e32 v9, v11
	v_pk_add_f32 v[4:5], v[150:151], v[4:5]
	v_pk_fma_f32 v[0:1], v[2:3], v[72:73], v[0:1] op_sel_hi:[1,0,1]
	v_cvt_pk_bf16_f32 v4, v4, v5
	ds_write_b16 v58, v4 offset:30464
	ds_write_b16_d16_hi v58, v4 offset:30736
	v_lshlrev_b32_e32 v4, 8, v10
	v_or3_b32 v4, v156, v157, v4
	v_lshl_or_b32 v5, v9, 24, v4
	ds_write_b16 v68, v4 offset:65280
	v_add_u32_e32 v4, 0x10010, v68
	ds_write_b16_d16_hi v4, v5
	v_pk_fma_f32 v[4:5], v[2:3], v[8:9], 0.5 op_sel_hi:[1,0,0]
	v_pk_add_f32 v[0:1], v[56:57], v[0:1]
	v_cvt_u32_f32_e32 v4, v4
	v_cvt_u32_f32_e32 v5, v5
	v_cvt_pk_bf16_f32 v0, v0, v1
	ds_write_b16 v58, v0 offset:31008
	ds_write_b16_d16_hi v58, v0 offset:31280
	v_lshlrev_b32_e32 v0, 8, v4
	v_add_u32_e32 v2, 0, v53
	v_or3_b32 v0, v163, v179, v0
	v_add_u32_e32 v2, 0x7920, v2
	v_lshl_or_b32 v1, v5, 24, v0
	ds_write_b16 v2, v0 offset:34816
	ds_write_b16_d16_hi v2, v1 offset:35088
	s_add_i32 s78, s69, s24
	s_cmpk_lt_i32 s78, 0x800
	s_cbranch_scc0 .Llru_nopre
	v_lshlrev_b32_e32 v250, 3, v202
	v_and_b32_e32 v250, 0x78, v250
	v_or_b32_e32 v250, s38, v250
	v_lshlrev_b32_e32 v250, 2, v250
	s_add_u32 s84, s20, 0x2000
	s_addc_u32 s85, s21, 0
	s_add_u32 s86, s20, 0x4000
	s_addc_u32 s87, s21, 0
	s_add_u32 s88, s20, 0x6000
	s_addc_u32 s89, s21, 0
	s_ashr_i32 s79, s78, 4
	v_and_b32_e32 v251, -4, v94
	v_lshl_add_u32 v251, s79, 7, v251
	v_add_u32_e32 v251, 4, v251
	global_load_dwordx4 v[12:15], v250, s[84:85]
	global_load_dwordx4 v[0:3], v250, s[84:85] offset:16
	global_load_dwordx4 v[32:35], v250, s[86:87]
	global_load_dwordx4 v[24:27], v250, s[86:87] offset:16
	global_load_dwordx4 v[16:19], v250, s[88:89]
	global_load_dwordx4 v[4:7], v250, s[88:89] offset:16
	global_load_dwordx4 v[28:31], v250, s[20:21] offset:16
	global_load_dwordx4 v[8:11], v250, s[22:23] offset:16
	global_load_dwordx4 v[36:39], v250, s[20:21]
	global_load_dwordx4 v[20:23], v250, s[22:23]
	global_load_dwordx4 v[40:43], v[248:249], off offset:-1024
	global_load_dwordx4 v[44:47], v[248:249], off offset:-512
	global_load_dwordx4 v[48:51], v[248:249], off
	global_load_dwordx4 v[52:55], v[248:249], off offset:512
	global_load_dwordx4 v[56:59], v[248:249], off offset:1024
	global_load_dwordx4 v[60:63], v[248:249], off offset:1536
	v_mov_b32_e32 v64, 0
	v_mov_b32_e32 v65, 0
	v_mov_b32_e32 v66, 0
	v_mov_b32_e32 v67, 0
	v_cmp_gt_u32_e32 vcc, s65, v251
	s_and_saveexec_b64 s[80:81], vcc
	global_load_dwordx4 v[64:67], v[248:249], off offset:2048
	s_or_b64 exec, exec, s[80:81]
	s_mov_b32 s71, 1
.Llru_nopre:
	s_lshl_b64 s[4:5], s[58:59], 19
	s_add_u32 s6, s16, s4
	v_lshlrev_b32_e32 v208, 6, v75
	s_addc_u32 s7, s17, s5
	s_lshl_b32 s8, s38, 1
	v_mul_lo_u32 v228, v94, s67
	v_and_b32_e32 v68, 0xc0, v208
	s_add_u32 s6, s6, s8
	v_add3_u32 v229, s68, v228, v68
	s_waitcnt lgkmcnt(0)
	s_barrier
	s_addc_u32 s7, s7, 0
	ds_read_b128 v[208:211], v229
	ds_read_b128 v[212:215], v229 offset:16
	ds_read_b128 v[216:219], v229 offset:32
	ds_read_b128 v[220:223], v229 offset:48
	v_ashrrev_i32_e32 v95, 31, v94
	s_add_u32 s4, s43, s4
	v_lshlrev_b64 v[224:225], 12, v[94:95]
	s_addc_u32 s5, s45, s5
	v_lshl_add_u64 v[226:227], s[6:7], 0, v[224:225]
	s_add_u32 s4, s4, s8
	v_lshl_add_u64 v[226:227], v[226:227], 0, v[68:69]
	s_addc_u32 s5, s5, 0
	s_waitcnt lgkmcnt(3)
	global_store_dwordx4 v[226:227], v[208:211], off
	s_waitcnt lgkmcnt(2)
	global_store_dwordx4 v[226:227], v[212:215], off offset:16
	s_waitcnt lgkmcnt(1)
	global_store_dwordx4 v[226:227], v[216:219], off offset:32
	s_waitcnt lgkmcnt(0)
	global_store_dwordx4 v[226:227], v[220:223], off offset:48
	s_add_i32 s69, s69, s24
	s_cmpk_lt_i32 s69, 0x800
	v_add3_u32 v230, 0, v228, v68
	v_lshl_add_u64 v[232:233], s[4:5], 0, v[224:225]
	ds_read_b128 v[208:211], v230 offset:34816
	ds_read_b128 v[212:215], v230 offset:34832
	ds_read_b128 v[216:219], v230 offset:34848
	v_lshl_add_u64 v[224:225], v[232:233], 0, v[68:69]
	ds_read_b128 v[220:223], v230 offset:34864
	s_waitcnt lgkmcnt(3)
	global_store_dwordx4 v[224:225], v[208:211], off
	s_waitcnt lgkmcnt(2)
	global_store_dwordx4 v[224:225], v[212:215], off offset:16
	s_waitcnt lgkmcnt(1)
	global_store_dwordx4 v[224:225], v[216:219], off offset:32
	s_waitcnt lgkmcnt(0)
	global_store_dwordx4 v[224:225], v[220:223], off offset:48
	s_cbranch_scc0 .LBB0_232

; DI float bflo(unsigned w) { return __uint_as_float(w << 16); }
; DI float bfhi(unsigned w) { return __uint_as_float(w & 0xffff0000u); }
; DI void lru_tile(const Params& p, unsigned char* shm, int c, int nb, const LruPar par) {
;     ...
;         const int cgp = tid & 15, rg = tid >> 4, ch = nb * 128 + cgp * 8;
;         const float* cw = p.in[3]; const float* cb = p.in[4];
;         float w[4][8], bias[8];
; #pragma unroll
;         for (int tp = 0; tp < 4; ++tp) { const f32x4 a = *(const f32x4*)(cw + tp * 2048 + ch), b = *(const f32x4*)(cw + tp * 2048 + ch + 4);
;             w[tp][0] = a[0]; w[tp][1] = a[1]; w[tp][2] = a[2]; w[tp][3] = a[3]; w[tp][4] = b[0]; w[tp][5] = b[1]; w[tp][6] = b[2]; w[tp][7] = b[3]; }
;         { const f32x4 a = *(const f32x4*)(cb + ch), b = *(const f32x4*)(cb + ch + 4);
;             bias[0] = a[0]; bias[1] = a[1]; bias[2] = a[2]; bias[3] = a[3]; bias[4] = b[0]; bias[5] = b[1]; bias[6] = b[2]; bias[7] = b[3]; }
;         float xr[7][8];
; #pragma unroll
;         for (int k = 0; k < 7; ++k) { const int t = c * 128 + rg * 4 - 2 + k;
;             u32x4 v = {0u, 0u, 0u, 0u};
;             if (t >= 0 && t < S) v = *(const u32x4*)(ZU + (size_t)(nb >> 1) * S * 256 + (size_t)t * 256 + (nb & 1) * 128 + cgp * 8);
; #pragma unroll
;             for (int i = 0; i < 4; ++i) { xr[k][2 * i] = bflo(v[i]); xr[k][2 * i + 1] = bfhi(v[i]); } }
.LBB0_214:
	v_mov_b32_e32 v75, v202
	s_cmp_eq_u32 s71, 1
	s_cbranch_scc0 .Llru_load_now
	v_lshlrev_b32_e32 v98, 3, v75
	v_and_b32_e32 v98, 0x78, v98
	s_ashr_i32 s58, s69, 4
	v_ashrrev_i32_e32 v94, 2, v75
	v_and_b32_e32 v95, -4, v94
	v_readfirstlane_b32 s6, v75
	s_mov_b32 s82, 0x100000
	s_mov_b32 s83, 0
	v_lshl_add_u64 v[248:249], v[248:249], 0, s[82:83]
	s_waitcnt vmcnt(8)
	s_branch .Llru_rows_join
.Llru_load_now:
	s_lshl_b32 s4, s4, 22
	v_lshlrev_b32_e32 v0, 3, v75
	v_and_b32_e32 v98, 0x78, v0
	v_or_b32_e32 v0, s38, v98
	v_lshlrev_b32_e32 v68, 2, v0
	v_lshl_add_u64 v[4:5], s[20:21], 0, v[68:69]
	v_add_co_u32_e32 v2, vcc, s62, v4
	v_lshl_add_u64 v[0:1], v[4:5], 0, s[52:53]
	s_nop 0
	v_addc_co_u32_e32 v3, vcc, 0, v5, vcc
	v_add_co_u32_e32 v8, vcc, s65, v4
	v_lshl_add_u64 v[6:7], v[4:5], 0, s[54:55]
	s_nop 0
	v_addc_co_u32_e32 v9, vcc, 0, v5, vcc
	global_load_dwordx4 v[12:15], v[2:3], off
	s_nop 0
	global_load_dwordx4 v[0:3], v[0:1], off offset:16
	s_nop 0
	global_load_dwordx4 v[32:35], v[8:9], off
	global_load_dwordx4 v[24:27], v[6:7], off offset:16
	v_lshl_add_u64 v[6:7], v[4:5], 0, s[56:57]
	v_add_co_u32_e32 v4, vcc, s66, v4
	s_ashr_i32 s58, s69, 4
	s_nop 0
	v_addc_co_u32_e32 v5, vcc, 0, v5, vcc
	global_load_dwordx4 v[16:19], v[4:5], off
	s_nop 0
	global_load_dwordx4 v[4:7], v[6:7], off offset:16
	s_nop 0
	global_load_dwordx4 v[28:31], v68, s[20:21] offset:16
	global_load_dwordx4 v[8:11], v68, s[22:23] offset:16
	global_load_dwordx4 v[36:39], v68, s[20:21]
	global_load_dwordx4 v[20:23], v68, s[22:23]
	s_and_b32 s4, s4, 0x3800000
	s_add_u32 s4, s18, s4
	v_ashrrev_i32_e32 v94, 2, v75
	s_addc_u32 s5, s19, 0
	s_and_b32 s7, s38, 0x80
	v_and_b32_e32 v95, -4, v94
	s_lshl_b32 s7, s7, 1
	v_lshl_add_u32 v64, s58, 7, v95
	s_add_u32 s4, s4, s7
	v_add_u32_e32 v40, -2, v64
	s_addc_u32 s5, s5, 0
	v_lshlrev_b32_e32 v68, 1, v98
	v_readfirstlane_b32 s6, v75
	v_lshl_add_u64 v[96:97], s[4:5], 0, v[68:69]
	v_cmp_gt_u32_e32 vcc, s65, v40
	v_mov_b32_e32 v44, 0
	v_lshlrev_b32_e32 v68, 9, v40
	v_mov_b32_e32 v40, 0
	v_mov_b32_e32 v41, 0
	v_mov_b32_e32 v42, 0
	v_mov_b32_e32 v43, 0
	s_and_saveexec_b64 s[4:5], vcc
	s_cbranch_execz .LBB0_216
	v_lshl_add_u64 v[40:41], v[96:97], 0, v[68:69]
	global_load_dwordx4 v[40:43], v[40:41], off

; DI unsigned cvtpk(float lo, float hi) { unsigned r; asm volatile("v_cvt_pk_bf16_f32 %0, %1, %2" : "=v"(r) : "v"(lo), "v"(hi)); return r; }
; DI void lru_tile(const Params& p, unsigned char* shm, int c, int nb, const LruPar par) {
;     ...
;         for (int o = 0; o < 4; ++o) { float u8[8];
; #pragma unroll
;             for (int i = 0; i < 8; ++i) { float a = bias[i];
; #pragma unroll
;                 for (int tp = 0; tp < 4; ++tp) a += xr[o + tp][i] * w[tp][i];
;                 u8[i] = a; }
;             *(u32x4*)(UB + (rg * 4 + o) * LDU + cgp * 8) = (u32x4){cvtpk(u8[0], u8[1]), cvtpk(u8[2], u8[3]), cvtpk(u8[4], u8[5]), cvtpk(u8[6], u8[7])};
;     ...
;             for (int gt = 0; gt < 2; ++gt) bfr[s][gt] = *(const bf16x8*)(LWT + ((size_t)((d * 2 + gt) * 16 + nb) * 128 + chl) * 128 + s * 32 + q * 8);
.Llru_rows_join:
	v_and_b32_e32 v240, 0x3c0, v202
	v_lshrrev_b32_e32 v240, 2, v240
	v_and_or_b32 v240, v202, 15, v240
	v_add_u32_e32 v240, s38, v240
	v_bfe_u32 v241, v202, 4, 2
	v_lshlrev_b32_e32 v240, 8, v240
	v_lshl_add_u32 v240, v241, 4, v240
	s_add_u32 s72, s34, 0x80000
	s_addc_u32 s73, s35, 0
	global_load_dwordx4 v[208:211], v240, s[34:35]
	global_load_dwordx4 v[216:219], v240, s[34:35] offset:64
	global_load_dwordx4 v[212:215], v240, s[72:73]
	global_load_dwordx4 v[220:223], v240, s[72:73] offset:64
	global_load_dwordx4 v[224:227], v240, s[34:35] offset:128
	global_load_dwordx4 v[232:235], v240, s[34:35] offset:192
	global_load_dwordx4 v[228:231], v240, s[72:73] offset:128
	global_load_dwordx4 v[236:239], v240, s[72:73] offset:192
	v_lshlrev_b32_e32 v109, 16, v61
	v_and_b32_e32 v105, 0xffff0000, v61
	v_lshlrev_b32_e32 v97, 16, v63
	v_and_b32_e32 v61, 0xffff0000, v63
	v_lshlrev_b32_e32 v115, 16, v57
	v_and_b32_e32 v111, 0xffff0000, v57
	v_lshlrev_b32_e32 v107, 16, v58
	v_and_b32_e32 v103, 0xffff0000, v58
	v_lshlrev_b32_e32 v63, 16, v59
	v_and_b32_e32 v57, 0xffff0000, v59
	v_lshlrev_b32_e32 v133, 16, v53
	v_and_b32_e32 v131, 0xffff0000, v53
	v_lshlrev_b32_e32 v125, 16, v55
	v_and_b32_e32 v59, 0xffff0000, v55
	v_lshlrev_b32_e32 v124, 16, v51
	v_and_b32_e32 v58, 0xffff0000, v51
	v_lshlrev_b32_e32 v139, 16, v44
	v_lshlrev_b32_e32 v138, 16, v40
	v_lshlrev_b32_e32 v123, 16, v64
	v_and_b32_e32 v55, 0xffff0000, v64
	v_lshlrev_b32_e32 v53, 16, v65
	v_and_b32_e32 v51, 0xffff0000, v65
	v_mov_b32_e32 v64, v36
	v_mov_b32_e32 v65, v12
	v_lshlrev_b32_e32 v132, 16, v49
	v_and_b32_e32 v130, 0xffff0000, v49
	v_lshlrev_b32_e32 v143, 16, v45
	v_and_b32_e32 v145, 0xffff0000, v45
	v_lshlrev_b32_e32 v151, 16, v47
	v_and_b32_e32 v153, 0xffff0000, v47
	v_lshlrev_b32_e32 v150, 16, v43
	v_and_b32_e32 v152, 0xffff0000, v43
	v_lshlrev_b32_e32 v49, 16, v66
	v_and_b32_e32 v47, 0xffff0000, v66
	v_lshlrev_b32_e32 v45, 16, v67
	v_and_b32_e32 v43, 0xffff0000, v67
	v_pk_mul_f32 v[66:67], v[64:65], v[138:139]
	v_lshlrev_b32_e32 v137, 16, v52
	v_add_f32_e32 v12, v20, v66
	v_lshlrev_b32_e32 v136, 16, v48
	v_add_f32_e32 v12, v12, v67
	v_mov_b32_e32 v66, v32
	v_mov_b32_e32 v67, v16
	v_pk_mul_f32 v[154:155], v[66:67], v[136:137]
	v_and_b32_e32 v141, 0xffff0000, v44
	v_add_f32_e32 v12, v12, v154
	v_and_b32_e32 v140, 0xffff0000, v40
	v_lshlrev_b32_e32 v142, 16, v41
	v_and_b32_e32 v144, 0xffff0000, v41
	v_add_f32_e32 v41, v12, v155
	v_mov_b32_e32 v12, v37
	v_pk_mul_f32 v[36:37], v[12:13], v[140:141]
	v_and_b32_e32 v135, 0xffff0000, v52
	v_add_f32_e32 v16, v21, v36
	v_and_b32_e32 v134, 0xffff0000, v48
	v_add_f32_e32 v36, v16, v37
	v_mov_b32_e32 v16, v33
	v_pk_mul_f32 v[32:33], v[16:17], v[134:135]
	v_lshlrev_b32_e32 v146, 16, v42
	v_add_f32_e32 v32, v36, v32
	v_and_b32_e32 v148, 0xffff0000, v42
	v_add_f32_e32 v42, v32, v33
	v_mov_b32_e32 v32, v38
	v_mov_b32_e32 v33, v14
	v_pk_mul_f32 v[36:37], v[32:33], v[142:143]
	v_lshlrev_b32_e32 v147, 16, v46
	v_add_f32_e32 v14, v22, v36
	v_add_f32_e32 v14, v14, v37
	v_mov_b32_e32 v36, v34
	v_mov_b32_e32 v37, v18
	v_pk_mul_f32 v[154:155], v[36:37], v[132:133]
	v_and_b32_e32 v149, 0xffff0000, v46
	v_add_f32_e32 v14, v14, v154
	v_add_f32_e32 v44, v14, v155
	v_mov_b32_e32 v14, v39
	v_pk_mul_f32 v[38:39], v[14:15], v[144:145]
	v_lshlrev_b32_e32 v129, 16, v54
	v_add_f32_e32 v18, v23, v38
	v_add_f32_e32 v38, v18, v39
	v_mov_b32_e32 v18, v35
	v_pk_mul_f32 v[34:35], v[18:19], v[130:131]
	v_lshlrev_b32_e32 v128, 16, v50
	v_add_f32_e32 v34, v38, v34
	v_add_f32_e32 v46, v34, v35
	v_mov_b32_e32 v34, v28
	v_mov_b32_e32 v35, v0
	v_pk_mul_f32 v[38:39], v[34:35], v[146:147]
	v_and_b32_e32 v127, 0xffff0000, v54
	v_add_f32_e32 v0, v8, v38
	v_add_f32_e32 v0, v0, v39
	v_mov_b32_e32 v38, v24
	v_mov_b32_e32 v39, v4
	v_pk_mul_f32 v[154:155], v[38:39], v[128:129]
	v_and_b32_e32 v126, 0xffff0000, v50
	v_add_f32_e32 v0, v0, v154
	v_add_f32_e32 v48, v0, v155
	v_mov_b32_e32 v0, v29
	v_pk_mul_f32 v[28:29], v[0:1], v[148:149]
	v_mov_b32_e32 v154, v26
	v_add_f32_e32 v4, v9, v28
	v_add_f32_e32 v28, v4, v29
	v_mov_b32_e32 v4, v25
	v_pk_mul_f32 v[24:25], v[4:5], v[126:127]
	v_mov_b32_e32 v29, v2
	v_add_f32_e32 v24, v28, v24
	v_mov_b32_e32 v28, v30
	v_add_f32_e32 v50, v24, v25
	v_pk_mul_f32 v[24:25], v[28:29], v[150:151]
	v_mov_b32_e32 v155, v6
	v_add_f32_e32 v2, v10, v24
	v_add_f32_e32 v2, v2, v25
	v_pk_mul_f32 v[24:25], v[154:155], v[124:125]
	v_lshl_add_u32 v40, v98, 1, 0
	v_add_f32_e32 v2, v2, v24
	v_add_f32_e32 v30, v2, v25
	v_mov_b32_e32 v2, v31
	v_pk_mul_f32 v[24:25], v[2:3], v[152:153]
	s_ashr_i32 s4, s6, 6
	v_add_f32_e32 v6, v11, v24
	v_add_f32_e32 v26, v6, v25
	v_mov_b32_e32 v6, v27
	v_pk_mul_f32 v[24:25], v[6:7], v[58:59]
	v_lshlrev_b32_e32 v121, 16, v56
	v_add_f32_e32 v24, v26, v24
	v_add_f32_e32 v27, v24, v25
	v_cvt_pk_bf16_f32 v24, v41, v42
	v_cvt_pk_bf16_f32 v25, v44, v46
	v_cvt_pk_bf16_f32 v26, v48, v50
	v_cvt_pk_bf16_f32 v27, v30, v27
	v_mad_u64_u32 v[30:31], s[6:7], v95, s67, v[40:41]
	ds_write_b128 v30, v[24:27]
	v_mov_b32_e32 v24, v139
	v_mov_b32_e32 v25, v136
	v_pk_mul_f32 v[24:25], v[64:65], v[24:25]
	v_mov_b32_e32 v120, v137
	v_add_f32_e32 v24, v20, v24
	v_add_f32_e32 v26, v24, v25
	v_pk_mul_f32 v[24:25], v[66:67], v[120:121]
	v_and_b32_e32 v119, 0xffff0000, v56
	v_add_f32_e32 v24, v26, v24
	v_add_f32_e32 v26, v24, v25
	v_mov_b32_e32 v24, v141
	v_mov_b32_e32 v25, v134
	v_pk_mul_f32 v[24:25], v[12:13], v[24:25]
	v_mov_b32_e32 v118, v135
	v_add_f32_e32 v24, v21, v24
	v_add_f32_e32 v27, v24, v25
	v_pk_mul_f32 v[24:25], v[16:17], v[118:119]
	v_mov_b32_e32 v114, v133
	v_add_f32_e32 v24, v27, v24
	v_add_f32_e32 v27, v24, v25
	v_mov_b32_e32 v24, v143
; DI unsigned cvtpk(float lo, float hi) { unsigned r; asm volatile("v_cvt_pk_bf16_f32 %0, %1, %2" : "=v"(r) : "v"(lo), "v"(hi)); return r; }
; DI void lru_tile(const Params& p, unsigned char* shm, int c, int nb, const LruPar par) {
;     ...
;         for (int o = 0; o < 4; ++o) { float u8[8];
; #pragma unroll
;             for (int i = 0; i < 8; ++i) { float a = bias[i];
; #pragma unroll
;                 for (int tp = 0; tp < 4; ++tp) a += xr[o + tp][i] * w[tp][i];
;                 u8[i] = a; }
;             *(u32x4*)(UB + (rg * 4 + o) * LDU + cgp * 8) = (u32x4){cvtpk(u8[0], u8[1]), cvtpk(u8[2], u8[3]), cvtpk(u8[4], u8[5]), cvtpk(u8[6], u8[7])};
;         }
;     }
;     __syncthreads();
	v_mov_b32_e32 v25, v132
	v_pk_mul_f32 v[24:25], v[32:33], v[24:25]
	v_mov_b32_e32 v110, v131
	v_add_f32_e32 v24, v22, v24
	v_add_f32_e32 v31, v24, v25
	v_pk_mul_f32 v[24:25], v[36:37], v[114:115]
	v_mov_b32_e32 v106, v129
	v_add_f32_e32 v24, v31, v24
	v_add_f32_e32 v31, v24, v25
	v_mov_b32_e32 v24, v145
	v_mov_b32_e32 v25, v130
	v_pk_mul_f32 v[24:25], v[14:15], v[24:25]
	v_mov_b32_e32 v102, v127
	v_add_f32_e32 v24, v23, v24
	v_add_f32_e32 v41, v24, v25
	v_pk_mul_f32 v[24:25], v[18:19], v[110:111]
	v_lshlrev_b32_e32 v101, 16, v62
	v_add_f32_e32 v24, v41, v24
	v_add_f32_e32 v41, v24, v25
	v_mov_b32_e32 v24, v147
	v_mov_b32_e32 v25, v128
	v_pk_mul_f32 v[24:25], v[34:35], v[24:25]
	v_and_b32_e32 v99, 0xffff0000, v62
	v_add_f32_e32 v24, v8, v24
	v_add_f32_e32 v42, v24, v25
	v_pk_mul_f32 v[24:25], v[38:39], v[106:107]
	v_mov_b32_e32 v62, v125
	v_add_f32_e32 v24, v42, v24
	v_add_f32_e32 v42, v24, v25
	v_mov_b32_e32 v24, v149
	v_mov_b32_e32 v25, v126
	v_pk_mul_f32 v[24:25], v[0:1], v[24:25]
	v_mov_b32_e32 v56, v59
	v_add_f32_e32 v24, v9, v24
	v_add_f32_e32 v44, v24, v25
	v_pk_mul_f32 v[24:25], v[4:5], v[102:103]
	v_lshlrev_b32_e32 v117, 16, v60
	v_add_f32_e32 v24, v44, v24
	v_add_f32_e32 v44, v24, v25
	v_mov_b32_e32 v24, v151
	v_mov_b32_e32 v25, v124
	v_pk_mul_f32 v[24:25], v[28:29], v[24:25]
	v_mov_b32_e32 v116, v121
	v_add_f32_e32 v24, v10, v24
	v_add_f32_e32 v46, v24, v25
	v_pk_mul_f32 v[24:25], v[154:155], v[62:63]
	v_and_b32_e32 v113, 0xffff0000, v60
	v_add_f32_e32 v24, v46, v24
	v_add_f32_e32 v46, v24, v25
	v_mov_b32_e32 v24, v153
	v_mov_b32_e32 v25, v58
	v_pk_mul_f32 v[24:25], v[2:3], v[24:25]
	v_mov_b32_e32 v112, v119
	v_add_f32_e32 v24, v11, v24
	v_add_f32_e32 v48, v24, v25
	v_pk_mul_f32 v[24:25], v[6:7], v[56:57]
	v_mov_b32_e32 v108, v115
	v_add_f32_e32 v24, v48, v24
	v_add_f32_e32 v48, v24, v25
	v_cvt_pk_bf16_f32 v24, v26, v27
	v_cvt_pk_bf16_f32 v25, v31, v41
	v_cvt_pk_bf16_f32 v26, v42, v44
	v_cvt_pk_bf16_f32 v27, v46, v48
	ds_write_b128 v30, v[24:27] offset:272
	v_pk_mul_f32 v[24:25], v[64:65], v[136:137]
	v_mov_b32_e32 v104, v111
	v_add_f32_e32 v24, v20, v24
	v_add_f32_e32 v26, v24, v25
	v_pk_mul_f32 v[24:25], v[66:67], v[116:117]
	v_mov_b32_e32 v100, v107
	v_add_f32_e32 v24, v26, v24
	v_add_f32_e32 v26, v24, v25
	v_pk_mul_f32 v[24:25], v[12:13], v[134:135]
	v_mov_b32_e32 v98, v103
	v_add_f32_e32 v24, v21, v24
	v_add_f32_e32 v27, v24, v25
	v_pk_mul_f32 v[24:25], v[16:17], v[112:113]
	v_mov_b32_e32 v96, v63
	v_add_f32_e32 v24, v27, v24
	v_add_f32_e32 v27, v24, v25
	v_pk_mul_f32 v[24:25], v[32:33], v[132:133]
	v_pk_mul_f32 v[12:13], v[12:13], v[118:119]
	v_add_f32_e32 v24, v22, v24
	v_add_f32_e32 v31, v24, v25
	v_pk_mul_f32 v[24:25], v[36:37], v[108:109]
	v_add_f32_e32 v12, v21, v12
	v_add_f32_e32 v24, v31, v24
	v_add_f32_e32 v31, v24, v25
	v_pk_mul_f32 v[24:25], v[14:15], v[130:131]
	v_mov_b32_e32 v54, v113
	v_add_f32_e32 v24, v23, v24
	v_add_f32_e32 v41, v24, v25
	v_pk_mul_f32 v[24:25], v[18:19], v[104:105]
	v_mov_b32_e32 v60, v57
	v_add_f32_e32 v24, v41, v24
	v_add_f32_e32 v41, v24, v25
	v_pk_mul_f32 v[24:25], v[34:35], v[128:129]
	v_add_f32_e32 v21, v12, v13
	v_add_f32_e32 v24, v8, v24
	v_add_f32_e32 v42, v24, v25
	v_pk_mul_f32 v[24:25], v[38:39], v[100:101]
	v_pk_mul_f32 v[12:13], v[16:17], v[54:55]
	v_add_f32_e32 v24, v42, v24
	v_add_f32_e32 v42, v24, v25
	v_pk_mul_f32 v[24:25], v[0:1], v[126:127]
	v_add_f32_e32 v12, v21, v12
	v_add_f32_e32 v24, v9, v24
	v_add_f32_e32 v44, v24, v25
	v_pk_mul_f32 v[24:25], v[4:5], v[98:99]
	v_add_f32_e32 v16, v12, v13
	v_add_f32_e32 v24, v44, v24
	v_add_f32_e32 v44, v24, v25
	v_pk_mul_f32 v[24:25], v[28:29], v[124:125]
	v_pk_mul_f32 v[12:13], v[32:33], v[114:115]
	v_add_f32_e32 v24, v10, v24
	v_add_f32_e32 v46, v24, v25
	v_pk_mul_f32 v[24:25], v[154:155], v[96:97]
	v_pk_mul_f32 v[0:1], v[0:1], v[102:103]
	v_add_f32_e32 v24, v46, v24
	v_add_f32_e32 v46, v24, v25
	v_pk_mul_f32 v[24:25], v[2:3], v[58:59]
	v_add_f32_e32 v12, v22, v12
	v_add_f32_e32 v24, v11, v24
	v_add_f32_e32 v48, v24, v25
	v_pk_mul_f32 v[24:25], v[6:7], v[60:61]
	v_mov_b32_e32 v52, v109
	v_add_f32_e32 v24, v48, v24
	v_add_f32_e32 v48, v24, v25
	v_cvt_pk_bf16_f32 v24, v26, v27
	v_cvt_pk_bf16_f32 v25, v31, v41
	v_cvt_pk_bf16_f32 v26, v42, v44
	v_cvt_pk_bf16_f32 v27, v46, v48
	v_add_f32_e32 v0, v9, v0
	v_mov_b32_e32 v46, v99
	v_add_f32_e32 v17, v12, v13
	v_pk_mul_f32 v[12:13], v[36:37], v[52:53]
	v_add_f32_e32 v9, v0, v1
	v_pk_mul_f32 v[0:1], v[4:5], v[46:47]
	v_add_f32_e32 v12, v17, v12
	v_add_f32_e32 v0, v9, v0
	v_add_f32_e32 v17, v12, v13
	v_pk_mul_f32 v[12:13], v[14:15], v[110:111]
	v_add_f32_e32 v4, v0, v1
	v_pk_mul_f32 v[0:1], v[28:29], v[62:63]
	v_add_f32_e32 v12, v23, v12
	v_mov_b32_e32 v50, v105
	v_add_f32_e32 v0, v10, v0
	v_mov_b32_e32 v44, v97
	v_add_f32_e32 v14, v12, v13
	v_pk_mul_f32 v[12:13], v[18:19], v[50:51]
	v_add_f32_e32 v5, v0, v1
	v_pk_mul_f32 v[0:1], v[154:155], v[44:45]
	v_add_f32_e32 v12, v14, v12
	v_add_f32_e32 v0, v5, v0
	ds_write_b128 v30, v[24:27] offset:544
	v_pk_mul_f32 v[24:25], v[64:65], v[120:121]
	v_add_f32_e32 v14, v12, v13
	v_pk_mul_f32 v[12:13], v[34:35], v[106:107]
	v_add_f32_e32 v5, v0, v1
	v_pk_mul_f32 v[0:1], v[2:3], v[56:57]
	v_add_f32_e32 v20, v20, v24
	v_mov_b32_e32 v122, v117
	v_add_f32_e32 v8, v8, v12
	v_mov_b32_e32 v48, v101
	v_add_f32_e32 v0, v11, v0
	v_mov_b32_e32 v42, v61
	v_add_f32_e32 v20, v20, v25
	v_pk_mul_f32 v[24:25], v[66:67], v[122:123]
	v_add_f32_e32 v8, v8, v13
	v_pk_mul_f32 v[12:13], v[38:39], v[48:49]
	v_add_f32_e32 v2, v0, v1
	v_pk_mul_f32 v[0:1], v[6:7], v[42:43]
	v_and_b32_e32 v164, 15, v75
	v_add_f32_e32 v20, v20, v24
	v_add_f32_e32 v8, v8, v12
	v_add_f32_e32 v0, v2, v0
	v_lshl_or_b32 v48, s4, 4, v164
	s_lshl_b32 s4, s4, 12
	s_ashr_i32 s59, s58, 31
	v_add_f32_e32 v20, v20, v25
	v_add_f32_e32 v8, v8, v13
	v_add_f32_e32 v3, v0, v1
	v_cvt_pk_bf16_f32 v0, v20, v16
	v_cvt_pk_bf16_f32 v1, v17, v14
	v_cvt_pk_bf16_f32 v2, v8, v4
	v_or_b32_e32 v4, 3, v94
	s_add_i32 s8, s4, 0
	s_lshl_b64 s[4:5], s[58:59], 14
	v_cvt_pk_bf16_f32 v3, v5, v3
	v_mad_u64_u32 v[4:5], s[6:7], v4, s67, v[40:41]
	v_bfe_u32 v99, v75, 4, 2
	v_ashrrev_i32_e32 v49, 31, v48
	s_add_u32 s4, s37, s4
	ds_write_b128 v4, v[0:3]
	v_lshlrev_b32_e32 v68, 4, v99
	v_lshl_add_u64 v[0:1], v[48:49], 0, s[38:39]
	s_addc_u32 s5, s41, s5
	s_or_b32 s6, s38, 0x800
	s_mov_b32 s7, s39
	v_lshl_add_u64 v[160:161], s[34:35], 0, v[68:69]
	v_lshlrev_b64 v[0:1], 8, v[0:1]
	v_lshl_add_u64 v[8:9], v[48:49], 0, s[6:7]
	v_lshl_add_u64 v[66:67], v[160:161], 0, v[0:1]
	v_add_u32_e32 v165, 0, v68
	v_lshlrev_b64 v[8:9], 8, v[8:9]
	s_waitcnt lgkmcnt(0)
	s_barrier
; DI void lru_tile(const Params& p, unsigned char* shm, int c, int nb, const LruPar par) {
;     ...
;         bf16x8 bfr[4][2];
; #pragma unroll
;         for (int s = 0; s < 4; ++s)
; #pragma unroll
;             for (int gt = 0; gt < 2; ++gt) bfr[s][gt] = *(const bf16x8*)(LWT + ((size_t)((d * 2 + gt) * 16 + nb) * 128 + chl) * 128 + s * 32 + q * 8);
; #pragma unroll
;         for (int s = 0; s < 4; ++s) {
; #pragma unroll
;             for (int rt = 0; rt < 8; ++rt) {
;                 const bf16x8 af = *(const bf16x8*)(UB + (rt * 16 + col) * LDU + s * 32 + q * 8);
; #pragma unroll
;                 for (int gt = 0; gt < 2; ++gt) acc[gt][rt] = __builtin_amdgcn_mfma_f32_16x16x32_bf16(af, bfr[s][gt], acc[gt][rt], 0, 0, 0);
;             }
	v_mad_u32_u24 v68, v164, s67, v165
	v_lshl_add_u64 v[96:97], v[160:161], 0, v[8:9]
	ds_read_b128 v[4:7], v68
	ds_read_b128 v[12:15], v68 offset:4352
	ds_read_b128 v[32:35], v68 offset:8704
	ds_read_b128 v[36:39], v68 offset:13056
	ds_read_b128 v[50:53], v68 offset:17408
	ds_read_b128 v[54:57], v68 offset:21760
	ds_read_b128 v[58:61], v68 offset:26112
	ds_read_b128 v[116:119], v68 offset:30464
	s_waitcnt vmcnt(7) lgkmcnt(7)
	v_mfma_f32_16x16x32_bf16 v[16:19], v[4:7], v[208:211], 0
	v_cmp_eq_u32_e64 s[10:11], 0, v99
	s_waitcnt lgkmcnt(6)
	v_mfma_f32_16x16x32_bf16 v[28:31], v[12:15], v[208:211], 0
	s_waitcnt lgkmcnt(5)
	v_mfma_f32_16x16x32_bf16 v[40:43], v[32:35], v[208:211], 0
	s_waitcnt lgkmcnt(4)
	v_mfma_f32_16x16x32_bf16 v[44:47], v[36:39], v[208:211], 0
	s_waitcnt lgkmcnt(3)
	v_mfma_f32_16x16x32_bf16 v[62:65], v[50:53], v[208:211], 0
	s_waitcnt vmcnt(5)
	v_mfma_f32_16x16x32_bf16 v[50:53], v[50:53], v[212:215], 0
	s_waitcnt lgkmcnt(2)
	v_mfma_f32_16x16x32_bf16 v[100:103], v[54:57], v[208:211], 0
	v_mfma_f32_16x16x32_bf16 v[104:107], v[54:57], v[212:215], 0
	v_lshl_add_u32 v55, v164, 3, s8
	v_add_u32_e32 v54, s38, v48
	s_waitcnt lgkmcnt(1)
	v_mfma_f32_16x16x32_bf16 v[120:123], v[58:61], v[208:211], 0
	v_mfma_f32_16x16x32_bf16 v[132:135], v[58:61], v[212:215], 0
	v_add_u32_e32 v59, 0x19800, v55
	v_ashrrev_i32_e32 v55, 31, v54
	v_lshlrev_b32_e32 v58, 1, v48
	s_waitcnt lgkmcnt(0)
	v_mfma_f32_16x16x32_bf16 v[0:3], v[116:119], v[208:211], 0
	v_lshl_add_u32 v61, v99, 7, v59
	v_lshl_add_u64 v[56:57], v[54:55], 3, s[4:5]
	v_mfma_f32_16x16x32_bf16 v[4:7], v[4:7], v[212:215], 0
	v_mfma_f32_16x16x32_bf16 v[12:15], v[12:15], v[212:215], 0
	v_mfma_f32_16x16x32_bf16 v[32:35], v[32:35], v[212:215], 0
	v_mfma_f32_16x16x32_bf16 v[36:39], v[36:39], v[212:215], 0
	v_mfma_f32_16x16x32_bf16 v[20:23], v[116:119], v[212:215], 0
	ds_read_b128 v[116:119], v68 offset:64
	ds_read_b128 v[136:139], v68 offset:4416
	s_waitcnt lgkmcnt(1)
	v_mfma_f32_16x16x32_bf16 v[16:19], v[116:119], v[216:219], v[16:19]
	s_waitcnt vmcnt(4)
	v_mfma_f32_16x16x32_bf16 v[4:7], v[116:119], v[220:223], v[4:7]
	s_waitcnt lgkmcnt(0)
	v_mfma_f32_16x16x32_bf16 v[28:31], v[136:139], v[216:219], v[28:31]
	v_mfma_f32_16x16x32_bf16 v[12:15], v[136:139], v[220:223], v[12:15]
	ds_read_b128 v[116:119], v68 offset:8768
	ds_read_b128 v[136:139], v68 offset:13120
	s_waitcnt lgkmcnt(1)
	v_mfma_f32_16x16x32_bf16 v[40:43], v[116:119], v[216:219], v[40:43]
	v_mfma_f32_16x16x32_bf16 v[32:35], v[116:119], v[220:223], v[32:35]
	s_waitcnt lgkmcnt(0)
	v_mfma_f32_16x16x32_bf16 v[44:47], v[136:139], v[216:219], v[44:47]
	v_mfma_f32_16x16x32_bf16 v[36:39], v[136:139], v[220:223], v[36:39]
	ds_read_b128 v[116:119], v68 offset:17472
	ds_read_b128 v[136:139], v68 offset:21824
	s_waitcnt lgkmcnt(1)
	v_mfma_f32_16x16x32_bf16 v[62:65], v[116:119], v[216:219], v[62:65]
	v_mfma_f32_16x16x32_bf16 v[50:53], v[116:119], v[220:223], v[50:53]
	s_waitcnt lgkmcnt(0)
	v_mfma_f32_16x16x32_bf16 v[100:103], v[136:139], v[216:219], v[100:103]
	v_mfma_f32_16x16x32_bf16 v[104:107], v[136:139], v[220:223], v[104:107]
	ds_read_b128 v[116:119], v68 offset:26176
	ds_read_b128 v[136:139], v68 offset:30528
	s_waitcnt lgkmcnt(1)
	v_mfma_f32_16x16x32_bf16 v[120:123], v[116:119], v[216:219], v[120:123]
	v_mfma_f32_16x16x32_bf16 v[116:119], v[116:119], v[220:223], v[132:135]
	s_waitcnt lgkmcnt(0)
	v_mfma_f32_16x16x32_bf16 v[0:3], v[136:139], v[216:219], v[0:3]
	v_mfma_f32_16x16x32_bf16 v[8:11], v[136:139], v[220:223], v[20:23]
	s_nop 2
	ds_read_b128 v[20:23], v68 offset:128
	ds_read_b128 v[24:27], v68 offset:4480
	s_waitcnt vmcnt(3) lgkmcnt(1)
	v_mfma_f32_16x16x32_bf16 v[16:19], v[20:23], v[224:227], v[16:19]
	s_waitcnt vmcnt(1)
	v_mfma_f32_16x16x32_bf16 v[4:7], v[20:23], v[228:231], v[4:7]
	s_waitcnt lgkmcnt(0)
	v_mfma_f32_16x16x32_bf16 v[20:23], v[24:27], v[224:227], v[28:31]
	v_mfma_f32_16x16x32_bf16 v[12:15], v[24:27], v[228:231], v[12:15]
	ds_read_b128 v[24:27], v68 offset:8832
	s_nop 0
	ds_read_b128 v[28:31], v68 offset:13184
	s_waitcnt lgkmcnt(1)
	v_mfma_f32_16x16x32_bf16 v[40:43], v[24:27], v[224:227], v[40:43]
	v_mfma_f32_16x16x32_bf16 v[24:27], v[24:27], v[228:231], v[32:35]
	s_waitcnt lgkmcnt(0)
	v_mfma_f32_16x16x32_bf16 v[32:35], v[28:31], v[224:227], v[44:47]
	v_mfma_f32_16x16x32_bf16 v[28:31], v[28:31], v[228:231], v[36:39]
	s_nop 2
	ds_read_b128 v[36:39], v68 offset:17536
	ds_read_b128 v[44:47], v68 offset:21888
	s_waitcnt lgkmcnt(1)
	v_mfma_f32_16x16x32_bf16 v[62:65], v[36:39], v[224:227], v[62:65]
	v_mfma_f32_16x16x32_bf16 v[50:53], v[36:39], v[228:231], v[50:53]
	s_waitcnt lgkmcnt(0)
	v_mfma_f32_16x16x32_bf16 v[100:103], v[44:47], v[224:227], v[100:103]
	v_mfma_f32_16x16x32_bf16 v[104:107], v[44:47], v[228:231], v[104:107]
	ds_read_b128 v[36:39], v68 offset:26240
	ds_read_b128 v[44:47], v68 offset:30592
	s_waitcnt lgkmcnt(1)
	v_mfma_f32_16x16x32_bf16 v[120:123], v[36:39], v[224:227], v[120:123]
	v_mfma_f32_16x16x32_bf16 v[116:119], v[36:39], v[228:231], v[116:119]
	s_waitcnt lgkmcnt(0)
	v_mfma_f32_16x16x32_bf16 v[0:3], v[44:47], v[224:227], v[0:3]
	v_mfma_f32_16x16x32_bf16 v[108:111], v[44:47], v[228:231], v[8:11]
	s_nop 2
	ds_read_b128 v[8:11], v68 offset:192
	ds_read_b128 v[36:39], v68 offset:4544
	s_waitcnt lgkmcnt(1)
	v_mfma_f32_16x16x32_bf16 v[124:127], v[8:11], v[232:235], v[16:19]
	s_waitcnt vmcnt(0)
	v_mfma_f32_16x16x32_bf16 v[132:135], v[8:11], v[236:239], v[4:7]
	s_nop 2
	ds_read_b128 v[4:7], v68 offset:8896
	ds_read_b128 v[8:11], v68 offset:13248
	s_waitcnt lgkmcnt(2)
	v_mfma_f32_16x16x32_bf16 v[136:139], v[36:39], v[232:235], v[20:23]
	v_mfma_f32_16x16x32_bf16 v[140:143], v[36:39], v[236:239], v[12:15]
	s_waitcnt lgkmcnt(1)
; DI float bf2f(unsigned short b) { return __uint_as_float(((unsigned)b) << 16); }
; DI float ex2(float x) { return __builtin_amdgcn_exp2f(x); }
; DI float rcpf_(float x) { return __builtin_amdgcn_rcpf(x); }
; DI void lru_tile(const Params& p, unsigned char* shm, int c, int nb, const LruPar par) {
;     ...
;         for (int s = 0; s < 4; ++s)
; #pragma unroll
;             for (int gt = 0; gt < 2; ++gt) bfr[s][gt] = *(const bf16x8*)(LWT + ((size_t)((d * 2 + gt) * 16 + nb) * 128 + chl) * 128 + s * 32 + q * 8);
; #pragma unroll
;         for (int s = 0; s < 4; ++s) {
; #pragma unroll
;             for (int rt = 0; rt < 8; ++rt) {
;                 const bf16x8 af = *(const bf16x8*)(UB + (rt * 16 + col) * LDU + s * 32 + q * 8);
; #pragma unroll
;                 for (int gt = 0; gt < 2; ++gt) acc[gt][rt] = __builtin_amdgcn_mfma_f32_16x16x32_bf16(af, bfr[s][gt], acc[gt][rt], 0, 0, 0);
;             }
;             __builtin_amdgcn_sched_barrier(0);
;         }
;         const f32x2 nl2 = {-LOG2E, -LOG2E}, nbr2 = {par.nbr[d], par.nbr[d]}, nbi2 = {par.nbi[d], par.nbi[d]}, cd2 = {par.cdec[d], par.cdec[d]}, one2 = {1.f, 1.f};
;         float hl[8][4], pc[8][4];
; #pragma unroll
;         for (int rt = 0; rt < 8; ++rt) {
;             float av[4], bv[4];
; #pragma unroll
;             for (int jp = 0; jp < 2; ++jp) {
;                 const f32x2 xr = {acc[0][rt][2 * jp], acc[0][rt][2 * jp + 1]}, xi = {acc[1][rt][2 * jp], acc[1][rt][2 * jp + 1]};
;                 f32x2 er = xr * nl2 + nbr2, ei = xi * nl2 + nbi2;
;                 er = (f32x2){ex2(er[0]), ex2(er[1])} + one2; ei = (f32x2){ex2(ei[0]), ex2(ei[1])} + one2;
;                 const f32x2 r = {rcpf_(er[0]), rcpf_(er[1])}, ig = {rcpf_(ei[0]), rcpf_(ei[1])};
;                 const f32x2 la = r * cd2;
;                 const f32x2 a = {ex2(la[0]), ex2(la[1])};
;                 const f32x2 om = one2 - a * a;
;                 const f32x2 sc = {__builtin_amdgcn_sqrtf(om[0]), __builtin_amdgcn_sqrtf(om[1])};
;                 const f32x2 u2 = {bf2f(UB[(rt * 16 + 4 * q + 2 * jp) * LDU + chl]), bf2f(UB[(rt * 16 + 4 * q + 2 * jp + 1) * LDU + chl])};
;                 const f32x2 b2 = sc * ig * u2;
;                 av[2 * jp] = a[0]; av[2 * jp + 1] = a[1]; bv[2 * jp] = b2[0]; bv[2 * jp + 1] = b2[1];
	v_mfma_f32_16x16x32_bf16 v[44:47], v[4:7], v[232:235], v[40:43]
	v_mfma_f32_16x16x32_bf16 v[40:43], v[4:7], v[236:239], v[24:27]
	s_waitcnt lgkmcnt(0)
	v_mfma_f32_16x16x32_bf16 v[36:39], v[8:11], v[232:235], v[32:35]
	v_mfma_f32_16x16x32_bf16 v[32:35], v[8:11], v[236:239], v[28:31]
	ds_read_b128 v[4:7], v68 offset:17600
	ds_read_b128 v[8:11], v68 offset:21952
	s_waitcnt lgkmcnt(1)
	v_mfma_f32_16x16x32_bf16 v[28:31], v[4:7], v[232:235], v[62:65]
	v_mfma_f32_16x16x32_bf16 v[24:27], v[4:7], v[236:239], v[50:53]
	ds_read_b128 v[4:7], v68 offset:26304
	s_nop 1
	ds_read_b128 v[50:53], v68 offset:30656
	s_waitcnt lgkmcnt(2)
	v_mfma_f32_16x16x32_bf16 v[20:23], v[8:11], v[232:235], v[100:103]
	v_mfma_f32_16x16x32_bf16 v[16:19], v[8:11], v[236:239], v[104:107]
	s_waitcnt lgkmcnt(1)
	v_mfma_f32_16x16x32_bf16 v[12:15], v[4:7], v[232:235], v[120:123]
	v_mfma_f32_16x16x32_bf16 v[8:11], v[4:7], v[236:239], v[116:119]
	s_waitcnt lgkmcnt(0)
	v_mfma_f32_16x16x32_bf16 v[4:7], v[50:53], v[232:235], v[0:3]
	v_mfma_f32_16x16x32_bf16 v[0:3], v[50:53], v[236:239], v[108:111]
	s_add_u32 s74, s34, 0x100000
	s_addc_u32 s75, s35, 0
	s_add_u32 s76, s34, 0x180000
	s_addc_u32 s77, s35, 0
	global_load_dwordx4 v[208:211], v240, s[74:75]
	global_load_dwordx4 v[216:219], v240, s[74:75] offset:64
	global_load_dwordx4 v[212:215], v240, s[76:77]
	global_load_dwordx4 v[220:223], v240, s[76:77] offset:64
	global_load_dwordx4 v[224:227], v240, s[74:75] offset:128
	global_load_dwordx4 v[228:231], v240, s[74:75] offset:192
	global_load_dwordx4 v[232:235], v240, s[76:77] offset:128
	global_load_dwordx4 v[236:239], v240, s[76:77] offset:192
	v_fma_f32 v52, -v126, s50, v82
	v_fma_f32 v53, -v127, s50, v82
	v_pk_fma_f32 v[54:55], v[134:135], s[50:51], v[86:87] op_sel_hi:[1,0,0] neg_lo:[1,0,0] neg_hi:[1,0,0]
	v_exp_f32_e32 v52, v52
	v_exp_f32_e32 v53, v53
	v_pk_fma_f32 v[50:51], v[124:125], s[50:51], v[82:83] op_sel_hi:[1,0,0] neg_lo:[1,0,0] neg_hi:[1,0,0]
	v_exp_f32_e32 v54, v54
	v_exp_f32_e32 v55, v55
	v_pk_add_f32 v[52:53], v[52:53], 1.0 op_sel_hi:[1,0]
	v_exp_f32_e32 v50, v50
	v_rcp_f32_e32 v52, v52
	v_rcp_f32_e32 v53, v53
	v_exp_f32_e32 v51, v51
	v_mul_u32_u24_e32 v95, 0x220, v99
	v_lshlrev_b32_e32 v60, 1, v95
	v_pk_mul_f32 v[52:53], v[92:93], v[52:53] op_sel_hi:[0,1]
	v_exp_f32_e32 v62, v52
	v_exp_f32_e32 v63, v53
	v_pk_add_f32 v[52:53], v[54:55], 1.0 op_sel_hi:[1,0]
	v_pk_add_f32 v[50:51], v[50:51], 1.0 op_sel_hi:[1,0]
	v_rcp_f32_e32 v52, v52
	v_pk_fma_f32 v[54:55], v[62:63], v[62:63], 1.0 op_sel_hi:[1,1,0] neg_lo:[1,0,0] neg_hi:[1,0,0]
	v_rcp_f32_e32 v53, v53
	v_sqrt_f32_e32 v54, v54
	v_sqrt_f32_e32 v55, v55
	v_rcp_f32_e32 v50, v50
	v_rcp_f32_e32 v51, v51
	v_add3_u32 v68, 0, v58, v60
	v_pk_mul_f32 v[52:53], v[52:53], v[54:55]
	v_pk_fma_f32 v[54:55], v[132:133], s[50:51], v[86:87] op_sel_hi:[1,0,0] neg_lo:[1,0,0] neg_hi:[1,0,0]
	v_pk_mul_f32 v[50:51], v[92:93], v[50:51] op_sel_hi:[0,1]
	v_exp_f32_e32 v54, v54
	v_exp_f32_e32 v55, v55
	v_exp_f32_e32 v50, v50
	v_exp_f32_e32 v51, v51
	v_add3_u32 v97, 0, v60, v58
	ds_read_u16 v58, v68 offset:544
	ds_read_u16 v60, v97 offset:816
	v_pk_add_f32 v[54:55], v[54:55], 1.0 op_sel_hi:[1,0]
	ds_read_u16 v96, v97 offset:272
	ds_read_u16 v98, v68
	v_rcp_f32_e32 v64, v54
	v_rcp_f32_e32 v65, v55
	v_pk_fma_f32 v[54:55], v[50:51], v[50:51], 1.0 op_sel_hi:[1,1,0] neg_lo:[1,0,0] neg_hi:[1,0,0]
	s_nop 0
	v_sqrt_f32_e32 v66, v54
	v_sqrt_f32_e32 v67, v55
	s_waitcnt lgkmcnt(3)
	v_lshlrev_b32_e32 v54, 16, v58
	s_waitcnt lgkmcnt(2)
	v_lshlrev_b32_e32 v55, 16, v60
	v_pk_mul_f32 v[54:55], v[52:53], v[54:55]
	v_pk_mul_f32 v[52:53], v[64:65], v[66:67]
	s_waitcnt lgkmcnt(0)
	v_lshlrev_b32_e32 v64, 16, v98
	v_lshlrev_b32_e32 v65, 16, v96
	v_pk_mul_f32 v[52:53], v[52:53], v[64:65]
	s_nop 0
	v_fma_f32 v52, 0, v50, v52
	v_fmac_f32_e32 v53, v51, v52
	v_mul_f32_e32 v51, v50, v51
	v_fma_f32 v58, v62, v53, v54
	v_mul_f32_e32 v60, v62, v51
	v_fmac_f32_e32 v55, v63, v58
	v_mul_f32_e32 v54, v63, v60
	ds_write_b64 v61, v[54:55]
	v_pk_fma_f32 v[64:65], v[138:139], s[50:51], v[82:83] op_sel_hi:[1,0,0] neg_lo:[1,0,0] neg_hi:[1,0,0]
	v_pk_fma_f32 v[66:67], v[142:143], s[50:51], v[86:87] op_sel_hi:[1,0,0] neg_lo:[1,0,0] neg_hi:[1,0,0]
	v_exp_f32_e32 v64, v64
	v_exp_f32_e32 v65, v65
	v_pk_fma_f32 v[62:63], v[136:137], s[50:51], v[82:83] op_sel_hi:[1,0,0] neg_lo:[1,0,0] neg_hi:[1,0,0]
	v_exp_f32_e32 v66, v66
	v_exp_f32_e32 v67, v67
	v_pk_add_f32 v[64:65], v[64:65], 1.0 op_sel_hi:[1,0]
	v_exp_f32_e32 v62, v62
	v_rcp_f32_e32 v64, v64
	v_rcp_f32_e32 v65, v65
	v_exp_f32_e32 v63, v63
	ds_read_u16 v96, v68 offset:4896
	ds_read_u16 v98, v97 offset:5168
	ds_read_u16 v106, v97 offset:4624
	ds_read_u16 v107, v68 offset:4352
	v_pk_mul_f32 v[64:65], v[92:93], v[64:65] op_sel_hi:[0,1]
	v_exp_f32_e32 v100, v64
	v_exp_f32_e32 v101, v65
	v_pk_add_f32 v[64:65], v[66:67], 1.0 op_sel_hi:[1,0]
	v_pk_add_f32 v[62:63], v[62:63], 1.0 op_sel_hi:[1,0]
	v_rcp_f32_e32 v64, v64
	v_pk_fma_f32 v[66:67], v[100:101], v[100:101], 1.0 op_sel_hi:[1,1,0] neg_lo:[1,0,0] neg_hi:[1,0,0]
	v_rcp_f32_e32 v65, v65
	v_sqrt_f32_e32 v66, v66
	v_sqrt_f32_e32 v67, v67
	v_rcp_f32_e32 v62, v62
	v_rcp_f32_e32 v63, v63
	v_pk_mul_f32 v[64:65], v[64:65], v[66:67]
	v_pk_fma_f32 v[66:67], v[140:141], s[50:51], v[86:87] op_sel_hi:[1,0,0] neg_lo:[1,0,0] neg_hi:[1,0,0]
	v_pk_mul_f32 v[62:63], v[92:93], v[62:63] op_sel_hi:[0,1]
	v_exp_f32_e32 v66, v66
	v_exp_f32_e32 v67, v67
	v_exp_f32_e32 v62, v62
	v_exp_f32_e32 v63, v63
	v_pk_add_f32 v[66:67], v[66:67], 1.0 op_sel_hi:[1,0]
	s_nop 0
	v_rcp_f32_e32 v102, v66
	v_rcp_f32_e32 v103, v67
	v_pk_fma_f32 v[66:67], v[62:63], v[62:63], 1.0 op_sel_hi:[1,1,0] neg_lo:[1,0,0] neg_hi:[1,0,0]
	s_nop 0
	v_sqrt_f32_e32 v104, v66
	v_sqrt_f32_e32 v105, v67
	s_waitcnt lgkmcnt(3)
; DI float bf2f(unsigned short b) { return __uint_as_float(((unsigned)b) << 16); }
; DI float ex2(float x) { return __builtin_amdgcn_exp2f(x); }
; DI float rcpf_(float x) { return __builtin_amdgcn_rcpf(x); }
; DI void lru_tile(const Params& p, unsigned char* shm, int c, int nb, const LruPar par) {
;     ...
;         for (int rt = 0; rt < 8; ++rt) {
;             float av[4], bv[4];
; #pragma unroll
;             for (int jp = 0; jp < 2; ++jp) {
;                 const f32x2 xr = {acc[0][rt][2 * jp], acc[0][rt][2 * jp + 1]}, xi = {acc[1][rt][2 * jp], acc[1][rt][2 * jp + 1]};
;                 f32x2 er = xr * nl2 + nbr2, ei = xi * nl2 + nbi2;
;                 er = (f32x2){ex2(er[0]), ex2(er[1])} + one2; ei = (f32x2){ex2(ei[0]), ex2(ei[1])} + one2;
;                 const f32x2 r = {rcpf_(er[0]), rcpf_(er[1])}, ig = {rcpf_(ei[0]), rcpf_(ei[1])};
;                 const f32x2 la = r * cd2;
;                 const f32x2 a = {ex2(la[0]), ex2(la[1])};
;                 const f32x2 om = one2 - a * a;
;                 const f32x2 sc = {__builtin_amdgcn_sqrtf(om[0]), __builtin_amdgcn_sqrtf(om[1])};
;                 const f32x2 u2 = {bf2f(UB[(rt * 16 + 4 * q + 2 * jp) * LDU + chl]), bf2f(UB[(rt * 16 + 4 * q + 2 * jp + 1) * LDU + chl])};
;                 const f32x2 b2 = sc * ig * u2;
;                 av[2 * jp] = a[0]; av[2 * jp + 1] = a[1]; bv[2 * jp] = b2[0]; bv[2 * jp + 1] = b2[1];
;             }
;             float h = 0.f, P = 1.f;
;             if (d == 0) {
; #pragma unroll
;                 for (int j = 0; j < 4; ++j) { h = fmaf(av[j], h, bv[j]); P *= av[j]; hl[rt][j] = h; pc[rt][j] = P; }
;             } else {
; #pragma unroll
;                 for (int j = 3; j >= 0; --j) { h = fmaf(av[j], h, bv[j]); P *= av[j]; hl[rt][j] = h; pc[rt][j] = P; }
;             }
;             AG[(rt * 4 + q) * 16 + col] = (f32x2){P, h};
;             __builtin_amdgcn_sched_barrier(0);
	v_lshlrev_b32_e32 v66, 16, v96
	s_waitcnt lgkmcnt(2)
	v_lshlrev_b32_e32 v67, 16, v98
	v_pk_mul_f32 v[66:67], v[64:65], v[66:67]
	v_pk_mul_f32 v[64:65], v[102:103], v[104:105]
	s_waitcnt lgkmcnt(0)
	v_lshlrev_b32_e32 v102, 16, v107
	v_lshlrev_b32_e32 v103, 16, v106
	v_pk_mul_f32 v[64:65], v[64:65], v[102:103]
	s_nop 0
	v_fma_f32 v64, 0, v62, v64
	v_fmac_f32_e32 v65, v63, v64
	v_mul_f32_e32 v63, v62, v63
	v_fma_f32 v96, v100, v65, v66
	v_mul_f32_e32 v98, v100, v63
	v_fmac_f32_e32 v67, v101, v96
	v_mul_f32_e32 v66, v101, v98
	ds_write_b64 v61, v[66:67] offset:512
	v_pk_fma_f32 v[46:47], v[46:47], s[50:51], v[82:83] op_sel_hi:[1,0,0] neg_lo:[1,0,0] neg_hi:[1,0,0]
	v_pk_fma_f32 v[44:45], v[44:45], s[50:51], v[82:83] op_sel_hi:[1,0,0] neg_lo:[1,0,0] neg_hi:[1,0,0]
	v_exp_f32_e32 v46, v46
	v_exp_f32_e32 v47, v47
	v_exp_f32_e32 v44, v44
	v_exp_f32_e32 v45, v45
	v_pk_fma_f32 v[42:43], v[42:43], s[50:51], v[86:87] op_sel_hi:[1,0,0] neg_lo:[1,0,0] neg_hi:[1,0,0]
	v_pk_add_f32 v[46:47], v[46:47], 1.0 op_sel_hi:[1,0]
	v_exp_f32_e32 v42, v42
	v_rcp_f32_e32 v46, v46
	v_rcp_f32_e32 v47, v47
	v_pk_add_f32 v[44:45], v[44:45], 1.0 op_sel_hi:[1,0]
	v_exp_f32_e32 v43, v43
	v_rcp_f32_e32 v44, v44
	v_pk_mul_f32 v[46:47], v[92:93], v[46:47] op_sel_hi:[0,1]
	v_exp_f32_e32 v46, v46
	v_exp_f32_e32 v47, v47
	v_rcp_f32_e32 v45, v45
	v_pk_add_f32 v[42:43], v[42:43], 1.0 op_sel_hi:[1,0]
	v_pk_fma_f32 v[40:41], v[40:41], s[50:51], v[86:87] op_sel_hi:[1,0,0] neg_lo:[1,0,0] neg_hi:[1,0,0]
	v_pk_fma_f32 v[100:101], v[46:47], v[46:47], 1.0 op_sel_hi:[1,1,0] neg_lo:[1,0,0] neg_hi:[1,0,0]
	v_rcp_f32_e32 v42, v42
	v_rcp_f32_e32 v43, v43
	v_sqrt_f32_e32 v102, v100
	v_sqrt_f32_e32 v103, v101
	v_pk_mul_f32 v[44:45], v[92:93], v[44:45] op_sel_hi:[0,1]
	v_exp_f32_e32 v100, v44
	v_exp_f32_e32 v40, v40
	v_exp_f32_e32 v41, v41
	v_exp_f32_e32 v101, v45
	v_pk_mul_f32 v[42:43], v[42:43], v[102:103]
	ds_read_u16 v102, v68 offset:9248
	ds_read_u16 v103, v97 offset:9520
	v_pk_add_f32 v[40:41], v[40:41], 1.0 op_sel_hi:[1,0]
	v_pk_fma_f32 v[44:45], v[100:101], v[100:101], 1.0 op_sel_hi:[1,1,0] neg_lo:[1,0,0] neg_hi:[1,0,0]
	ds_read_u16 v106, v97 offset:8976
	ds_read_u16 v107, v68 offset:8704
	v_rcp_f32_e32 v40, v40
	v_rcp_f32_e32 v41, v41
	v_sqrt_f32_e32 v44, v44
	v_sqrt_f32_e32 v45, v45
	s_waitcnt lgkmcnt(3)
	v_lshlrev_b32_e32 v102, 16, v102
	s_waitcnt lgkmcnt(2)
	v_lshlrev_b32_e32 v103, 16, v103
	v_pk_mul_f32 v[104:105], v[42:43], v[102:103]
	v_pk_mul_f32 v[40:41], v[40:41], v[44:45]
	s_waitcnt lgkmcnt(0)
	v_lshlrev_b32_e32 v42, 16, v107
	v_lshlrev_b32_e32 v43, 16, v106
	v_pk_mul_f32 v[102:103], v[40:41], v[42:43]
	s_nop 0
	v_fma_f32 v102, 0, v100, v102
	v_fmac_f32_e32 v103, v101, v102
	v_mul_f32_e32 v101, v100, v101
	v_fma_f32 v106, v46, v103, v104
	v_mul_f32_e32 v108, v46, v101
	v_fmac_f32_e32 v105, v47, v106
	v_mul_f32_e32 v104, v47, v108
	ds_write_b64 v61, v[104:105] offset:1024
	v_pk_fma_f32 v[38:39], v[38:39], s[50:51], v[82:83] op_sel_hi:[1,0,0] neg_lo:[1,0,0] neg_hi:[1,0,0]
	v_pk_fma_f32 v[36:37], v[36:37], s[50:51], v[82:83] op_sel_hi:[1,0,0] neg_lo:[1,0,0] neg_hi:[1,0,0]
	v_exp_f32_e32 v38, v38
	v_exp_f32_e32 v39, v39
	v_exp_f32_e32 v36, v36
	v_exp_f32_e32 v37, v37
	v_pk_fma_f32 v[34:35], v[34:35], s[50:51], v[86:87] op_sel_hi:[1,0,0] neg_lo:[1,0,0] neg_hi:[1,0,0]
	v_pk_add_f32 v[38:39], v[38:39], 1.0 op_sel_hi:[1,0]
	v_exp_f32_e32 v34, v34
	v_rcp_f32_e32 v38, v38
	v_rcp_f32_e32 v39, v39
	v_pk_add_f32 v[36:37], v[36:37], 1.0 op_sel_hi:[1,0]
	v_exp_f32_e32 v35, v35
	v_rcp_f32_e32 v36, v36
	v_pk_mul_f32 v[38:39], v[92:93], v[38:39] op_sel_hi:[0,1]
	v_exp_f32_e32 v38, v38
	v_exp_f32_e32 v39, v39
	v_rcp_f32_e32 v37, v37
	v_pk_add_f32 v[34:35], v[34:35], 1.0 op_sel_hi:[1,0]
	v_pk_fma_f32 v[32:33], v[32:33], s[50:51], v[86:87] op_sel_hi:[1,0,0] neg_lo:[1,0,0] neg_hi:[1,0,0]
	v_pk_fma_f32 v[40:41], v[38:39], v[38:39], 1.0 op_sel_hi:[1,1,0] neg_lo:[1,0,0] neg_hi:[1,0,0]
	v_rcp_f32_e32 v34, v34
	v_rcp_f32_e32 v35, v35
	v_sqrt_f32_e32 v40, v40
	v_sqrt_f32_e32 v41, v41
	v_pk_mul_f32 v[36:37], v[92:93], v[36:37] op_sel_hi:[0,1]
	v_exp_f32_e32 v110, v36
	v_exp_f32_e32 v32, v32
	v_exp_f32_e32 v33, v33
	v_exp_f32_e32 v111, v37
	v_pk_mul_f32 v[34:35], v[34:35], v[40:41]
	ds_read_u16 v40, v68 offset:13600
	ds_read_u16 v41, v97 offset:13872
	v_pk_add_f32 v[32:33], v[32:33], 1.0 op_sel_hi:[1,0]
	v_pk_fma_f32 v[36:37], v[110:111], v[110:111], 1.0 op_sel_hi:[1,1,0] neg_lo:[1,0,0] neg_hi:[1,0,0]
	ds_read_u16 v42, v97 offset:13328
	ds_read_u16 v43, v68 offset:13056
	v_rcp_f32_e32 v32, v32
	v_rcp_f32_e32 v33, v33
	v_sqrt_f32_e32 v36, v36
	v_sqrt_f32_e32 v37, v37
	s_waitcnt lgkmcnt(3)
	v_lshlrev_b32_e32 v40, 16, v40
	s_waitcnt lgkmcnt(2)
	v_lshlrev_b32_e32 v41, 16, v41
	v_pk_mul_f32 v[114:115], v[34:35], v[40:41]
	v_pk_mul_f32 v[32:33], v[32:33], v[36:37]
	s_waitcnt lgkmcnt(0)
; DI float bf2f(unsigned short b) { return __uint_as_float(((unsigned)b) << 16); }
; DI float ex2(float x) { return __builtin_amdgcn_exp2f(x); }
; DI float rcpf_(float x) { return __builtin_amdgcn_rcpf(x); }
; DI void lru_tile(const Params& p, unsigned char* shm, int c, int nb, const LruPar par) {
;     ...
;         for (int rt = 0; rt < 8; ++rt) {
;             float av[4], bv[4];
; #pragma unroll
;             for (int jp = 0; jp < 2; ++jp) {
;                 const f32x2 xr = {acc[0][rt][2 * jp], acc[0][rt][2 * jp + 1]}, xi = {acc[1][rt][2 * jp], acc[1][rt][2 * jp + 1]};
;                 f32x2 er = xr * nl2 + nbr2, ei = xi * nl2 + nbi2;
;                 er = (f32x2){ex2(er[0]), ex2(er[1])} + one2; ei = (f32x2){ex2(ei[0]), ex2(ei[1])} + one2;
;                 const f32x2 r = {rcpf_(er[0]), rcpf_(er[1])}, ig = {rcpf_(ei[0]), rcpf_(ei[1])};
;                 const f32x2 la = r * cd2;
;                 const f32x2 a = {ex2(la[0]), ex2(la[1])};
;                 const f32x2 om = one2 - a * a;
;                 const f32x2 sc = {__builtin_amdgcn_sqrtf(om[0]), __builtin_amdgcn_sqrtf(om[1])};
;                 const f32x2 u2 = {bf2f(UB[(rt * 16 + 4 * q + 2 * jp) * LDU + chl]), bf2f(UB[(rt * 16 + 4 * q + 2 * jp + 1) * LDU + chl])};
;                 const f32x2 b2 = sc * ig * u2;
;                 av[2 * jp] = a[0]; av[2 * jp + 1] = a[1]; bv[2 * jp] = b2[0]; bv[2 * jp + 1] = b2[1];
;             }
;             float h = 0.f, P = 1.f;
;             if (d == 0) {
; #pragma unroll
;                 for (int j = 0; j < 4; ++j) { h = fmaf(av[j], h, bv[j]); P *= av[j]; hl[rt][j] = h; pc[rt][j] = P; }
;             } else {
; #pragma unroll
;                 for (int j = 3; j >= 0; --j) { h = fmaf(av[j], h, bv[j]); P *= av[j]; hl[rt][j] = h; pc[rt][j] = P; }
;             }
;             AG[(rt * 4 + q) * 16 + col] = (f32x2){P, h};
;             __builtin_amdgcn_sched_barrier(0);
	v_lshlrev_b32_e32 v34, 16, v43
	v_lshlrev_b32_e32 v35, 16, v42
	v_pk_mul_f32 v[112:113], v[32:33], v[34:35]
	s_nop 0
	v_fma_f32 v112, 0, v110, v112
	v_fmac_f32_e32 v113, v111, v112
	v_mul_f32_e32 v111, v110, v111
	v_fma_f32 v116, v38, v113, v114
	v_mul_f32_e32 v118, v38, v111
	v_fmac_f32_e32 v115, v39, v116
	v_mul_f32_e32 v114, v39, v118
	ds_write_b64 v61, v[114:115] offset:1536
	v_pk_fma_f32 v[30:31], v[30:31], s[50:51], v[82:83] op_sel_hi:[1,0,0] neg_lo:[1,0,0] neg_hi:[1,0,0]
	v_pk_fma_f32 v[28:29], v[28:29], s[50:51], v[82:83] op_sel_hi:[1,0,0] neg_lo:[1,0,0] neg_hi:[1,0,0]
	v_exp_f32_e32 v30, v30
	v_exp_f32_e32 v31, v31
	v_exp_f32_e32 v28, v28
	v_exp_f32_e32 v29, v29
	v_pk_fma_f32 v[26:27], v[26:27], s[50:51], v[86:87] op_sel_hi:[1,0,0] neg_lo:[1,0,0] neg_hi:[1,0,0]
	v_pk_add_f32 v[30:31], v[30:31], 1.0 op_sel_hi:[1,0]
	v_exp_f32_e32 v26, v26
	v_rcp_f32_e32 v30, v30
	v_rcp_f32_e32 v31, v31
	v_pk_add_f32 v[28:29], v[28:29], 1.0 op_sel_hi:[1,0]
	v_exp_f32_e32 v27, v27
	v_rcp_f32_e32 v28, v28
	v_pk_mul_f32 v[30:31], v[92:93], v[30:31] op_sel_hi:[0,1]
	v_exp_f32_e32 v30, v30
	v_exp_f32_e32 v31, v31
	v_rcp_f32_e32 v29, v29
	v_pk_add_f32 v[26:27], v[26:27], 1.0 op_sel_hi:[1,0]
	v_pk_fma_f32 v[24:25], v[24:25], s[50:51], v[86:87] op_sel_hi:[1,0,0] neg_lo:[1,0,0] neg_hi:[1,0,0]
	v_pk_fma_f32 v[32:33], v[30:31], v[30:31], 1.0 op_sel_hi:[1,1,0] neg_lo:[1,0,0] neg_hi:[1,0,0]
	v_rcp_f32_e32 v26, v26
	v_rcp_f32_e32 v27, v27
	v_sqrt_f32_e32 v32, v32
	v_sqrt_f32_e32 v33, v33
	v_pk_mul_f32 v[28:29], v[92:93], v[28:29] op_sel_hi:[0,1]
	v_exp_f32_e32 v120, v28
	v_exp_f32_e32 v24, v24
	v_exp_f32_e32 v25, v25
	v_exp_f32_e32 v121, v29
	v_pk_mul_f32 v[26:27], v[26:27], v[32:33]
	ds_read_u16 v32, v68 offset:17952
	ds_read_u16 v33, v97 offset:18224
	v_pk_add_f32 v[24:25], v[24:25], 1.0 op_sel_hi:[1,0]
	v_pk_fma_f32 v[28:29], v[120:121], v[120:121], 1.0 op_sel_hi:[1,1,0] neg_lo:[1,0,0] neg_hi:[1,0,0]
	ds_read_u16 v34, v97 offset:17680
	ds_read_u16 v35, v68 offset:17408
	v_rcp_f32_e32 v24, v24
	v_rcp_f32_e32 v25, v25
	v_sqrt_f32_e32 v28, v28
	v_sqrt_f32_e32 v29, v29
	s_waitcnt lgkmcnt(3)
	v_lshlrev_b32_e32 v32, 16, v32
	s_waitcnt lgkmcnt(2)
	v_lshlrev_b32_e32 v33, 16, v33
	v_pk_mul_f32 v[124:125], v[26:27], v[32:33]
	v_pk_mul_f32 v[24:25], v[24:25], v[28:29]
	s_waitcnt lgkmcnt(0)
	v_lshlrev_b32_e32 v26, 16, v35
	v_lshlrev_b32_e32 v27, 16, v34
	v_pk_mul_f32 v[122:123], v[24:25], v[26:27]
	s_nop 0
	v_fma_f32 v122, 0, v120, v122
	v_fmac_f32_e32 v123, v121, v122
	v_mul_f32_e32 v121, v120, v121
	v_fma_f32 v126, v30, v123, v124
	v_mul_f32_e32 v128, v30, v121
	v_fmac_f32_e32 v125, v31, v126
	v_mul_f32_e32 v124, v31, v128
	ds_write_b64 v61, v[124:125] offset:2048
	v_pk_fma_f32 v[22:23], v[22:23], s[50:51], v[82:83] op_sel_hi:[1,0,0] neg_lo:[1,0,0] neg_hi:[1,0,0]
	v_pk_fma_f32 v[20:21], v[20:21], s[50:51], v[82:83] op_sel_hi:[1,0,0] neg_lo:[1,0,0] neg_hi:[1,0,0]
	v_exp_f32_e32 v22, v22
	v_exp_f32_e32 v23, v23
	v_exp_f32_e32 v20, v20
	v_exp_f32_e32 v21, v21
	v_pk_fma_f32 v[18:19], v[18:19], s[50:51], v[86:87] op_sel_hi:[1,0,0] neg_lo:[1,0,0] neg_hi:[1,0,0]
	v_pk_add_f32 v[22:23], v[22:23], 1.0 op_sel_hi:[1,0]
	v_exp_f32_e32 v18, v18
	v_rcp_f32_e32 v22, v22
	v_rcp_f32_e32 v23, v23
	v_pk_add_f32 v[20:21], v[20:21], 1.0 op_sel_hi:[1,0]
	v_exp_f32_e32 v19, v19
	v_rcp_f32_e32 v20, v20
	v_pk_mul_f32 v[22:23], v[92:93], v[22:23] op_sel_hi:[0,1]
	v_exp_f32_e32 v22, v22
	v_exp_f32_e32 v23, v23
	v_rcp_f32_e32 v21, v21
	v_pk_add_f32 v[18:19], v[18:19], 1.0 op_sel_hi:[1,0]
	v_pk_fma_f32 v[16:17], v[16:17], s[50:51], v[86:87] op_sel_hi:[1,0,0] neg_lo:[1,0,0] neg_hi:[1,0,0]
	v_pk_fma_f32 v[24:25], v[22:23], v[22:23], 1.0 op_sel_hi:[1,1,0] neg_lo:[1,0,0] neg_hi:[1,0,0]
	v_rcp_f32_e32 v18, v18
	v_rcp_f32_e32 v19, v19
	v_sqrt_f32_e32 v24, v24
	v_sqrt_f32_e32 v25, v25
	v_pk_mul_f32 v[20:21], v[92:93], v[20:21] op_sel_hi:[0,1]
	v_exp_f32_e32 v130, v20
	v_exp_f32_e32 v16, v16
	v_exp_f32_e32 v17, v17
	v_exp_f32_e32 v131, v21
	v_pk_mul_f32 v[18:19], v[18:19], v[24:25]
	ds_read_u16 v24, v68 offset:22304
	ds_read_u16 v25, v97 offset:22576
	v_pk_add_f32 v[16:17], v[16:17], 1.0 op_sel_hi:[1,0]
	v_pk_fma_f32 v[20:21], v[130:131], v[130:131], 1.0 op_sel_hi:[1,1,0] neg_lo:[1,0,0] neg_hi:[1,0,0]
	ds_read_u16 v26, v97 offset:22032
	ds_read_u16 v27, v68 offset:21760
	v_rcp_f32_e32 v16, v16
	v_rcp_f32_e32 v17, v17
	v_sqrt_f32_e32 v20, v20
	v_sqrt_f32_e32 v21, v21
	s_waitcnt lgkmcnt(3)
	v_lshlrev_b32_e32 v24, 16, v24
	s_waitcnt lgkmcnt(2)
	v_lshlrev_b32_e32 v25, 16, v25
	v_pk_mul_f32 v[134:135], v[18:19], v[24:25]
	v_pk_mul_f32 v[16:17], v[16:17], v[20:21]
	s_waitcnt lgkmcnt(0)
; DI float bf2f(unsigned short b) { return __uint_as_float(((unsigned)b) << 16); }
; DI float ex2(float x) { return __builtin_amdgcn_exp2f(x); }
; DI float rcpf_(float x) { return __builtin_amdgcn_rcpf(x); }
; DI void lru_tile(const Params& p, unsigned char* shm, int c, int nb, const LruPar par) {
;     ...
;         for (int rt = 0; rt < 8; ++rt) {
;             float av[4], bv[4];
; #pragma unroll
;             for (int jp = 0; jp < 2; ++jp) {
;                 const f32x2 xr = {acc[0][rt][2 * jp], acc[0][rt][2 * jp + 1]}, xi = {acc[1][rt][2 * jp], acc[1][rt][2 * jp + 1]};
;                 f32x2 er = xr * nl2 + nbr2, ei = xi * nl2 + nbi2;
;                 er = (f32x2){ex2(er[0]), ex2(er[1])} + one2; ei = (f32x2){ex2(ei[0]), ex2(ei[1])} + one2;
;                 const f32x2 r = {rcpf_(er[0]), rcpf_(er[1])}, ig = {rcpf_(ei[0]), rcpf_(ei[1])};
;                 const f32x2 la = r * cd2;
;                 const f32x2 a = {ex2(la[0]), ex2(la[1])};
;                 const f32x2 om = one2 - a * a;
;                 const f32x2 sc = {__builtin_amdgcn_sqrtf(om[0]), __builtin_amdgcn_sqrtf(om[1])};
;                 const f32x2 u2 = {bf2f(UB[(rt * 16 + 4 * q + 2 * jp) * LDU + chl]), bf2f(UB[(rt * 16 + 4 * q + 2 * jp + 1) * LDU + chl])};
;                 const f32x2 b2 = sc * ig * u2;
;                 av[2 * jp] = a[0]; av[2 * jp + 1] = a[1]; bv[2 * jp] = b2[0]; bv[2 * jp + 1] = b2[1];
;             }
;             float h = 0.f, P = 1.f;
;             if (d == 0) {
; #pragma unroll
;                 for (int j = 0; j < 4; ++j) { h = fmaf(av[j], h, bv[j]); P *= av[j]; hl[rt][j] = h; pc[rt][j] = P; }
;             } else {
; #pragma unroll
;                 for (int j = 3; j >= 0; --j) { h = fmaf(av[j], h, bv[j]); P *= av[j]; hl[rt][j] = h; pc[rt][j] = P; }
;             }
;             AG[(rt * 4 + q) * 16 + col] = (f32x2){P, h};
;             __builtin_amdgcn_sched_barrier(0);
;         }
;         asm volatile("s_waitcnt lgkmcnt(0)" ::: "memory");
	v_lshlrev_b32_e32 v18, 16, v27
	v_lshlrev_b32_e32 v19, 16, v26
	v_pk_mul_f32 v[132:133], v[16:17], v[18:19]
	s_nop 0
	v_fma_f32 v132, 0, v130, v132
	v_fmac_f32_e32 v133, v131, v132
	v_mul_f32_e32 v131, v130, v131
	v_fma_f32 v136, v22, v133, v134
	v_mul_f32_e32 v138, v22, v131
	v_fmac_f32_e32 v135, v23, v136
	v_mul_f32_e32 v134, v23, v138
	ds_write_b64 v61, v[134:135] offset:2560
	v_pk_fma_f32 v[14:15], v[14:15], s[50:51], v[82:83] op_sel_hi:[1,0,0] neg_lo:[1,0,0] neg_hi:[1,0,0]
	v_pk_fma_f32 v[12:13], v[12:13], s[50:51], v[82:83] op_sel_hi:[1,0,0] neg_lo:[1,0,0] neg_hi:[1,0,0]
	v_exp_f32_e32 v14, v14
	v_exp_f32_e32 v15, v15
	v_exp_f32_e32 v12, v12
	v_exp_f32_e32 v13, v13
	v_pk_fma_f32 v[10:11], v[10:11], s[50:51], v[86:87] op_sel_hi:[1,0,0] neg_lo:[1,0,0] neg_hi:[1,0,0]
	v_pk_add_f32 v[14:15], v[14:15], 1.0 op_sel_hi:[1,0]
	v_exp_f32_e32 v10, v10
	v_rcp_f32_e32 v14, v14
	v_rcp_f32_e32 v15, v15
	v_pk_add_f32 v[12:13], v[12:13], 1.0 op_sel_hi:[1,0]
	v_exp_f32_e32 v11, v11
	v_rcp_f32_e32 v12, v12
	v_pk_mul_f32 v[14:15], v[92:93], v[14:15] op_sel_hi:[0,1]
	v_exp_f32_e32 v14, v14
	v_exp_f32_e32 v15, v15
	v_rcp_f32_e32 v13, v13
	v_pk_add_f32 v[10:11], v[10:11], 1.0 op_sel_hi:[1,0]
	v_pk_fma_f32 v[8:9], v[8:9], s[50:51], v[86:87] op_sel_hi:[1,0,0] neg_lo:[1,0,0] neg_hi:[1,0,0]
	v_pk_fma_f32 v[16:17], v[14:15], v[14:15], 1.0 op_sel_hi:[1,1,0] neg_lo:[1,0,0] neg_hi:[1,0,0]
	v_rcp_f32_e32 v10, v10
	v_rcp_f32_e32 v11, v11
	v_sqrt_f32_e32 v16, v16
	v_sqrt_f32_e32 v17, v17
	v_pk_mul_f32 v[12:13], v[92:93], v[12:13] op_sel_hi:[0,1]
	v_exp_f32_e32 v140, v12
	v_exp_f32_e32 v8, v8
	v_exp_f32_e32 v9, v9
	v_exp_f32_e32 v141, v13
	v_pk_mul_f32 v[10:11], v[10:11], v[16:17]
	ds_read_u16 v16, v68 offset:26656
	ds_read_u16 v17, v97 offset:26928
	v_pk_add_f32 v[8:9], v[8:9], 1.0 op_sel_hi:[1,0]
	v_pk_fma_f32 v[12:13], v[140:141], v[140:141], 1.0 op_sel_hi:[1,1,0] neg_lo:[1,0,0] neg_hi:[1,0,0]
	ds_read_u16 v18, v97 offset:26384
	ds_read_u16 v19, v68 offset:26112
	v_rcp_f32_e32 v8, v8
	v_rcp_f32_e32 v9, v9
	v_sqrt_f32_e32 v12, v12
	v_sqrt_f32_e32 v13, v13
	s_waitcnt lgkmcnt(3)
	v_lshlrev_b32_e32 v16, 16, v16
	s_waitcnt lgkmcnt(2)
	v_lshlrev_b32_e32 v17, 16, v17
	v_pk_mul_f32 v[144:145], v[10:11], v[16:17]
	v_pk_mul_f32 v[8:9], v[8:9], v[12:13]
	s_waitcnt lgkmcnt(0)
	v_lshlrev_b32_e32 v10, 16, v19
	v_lshlrev_b32_e32 v11, 16, v18
	v_pk_mul_f32 v[142:143], v[8:9], v[10:11]
	s_nop 0
	v_fma_f32 v142, 0, v140, v142
	v_fmac_f32_e32 v143, v141, v142
	v_mul_f32_e32 v141, v140, v141
	v_fma_f32 v146, v14, v143, v144
	v_mul_f32_e32 v148, v14, v141
	v_fmac_f32_e32 v145, v15, v146
	v_mul_f32_e32 v144, v15, v148
	ds_write_b64 v61, v[144:145] offset:3072
	v_pk_fma_f32 v[6:7], v[6:7], s[50:51], v[82:83] op_sel_hi:[1,0,0] neg_lo:[1,0,0] neg_hi:[1,0,0]
	v_pk_fma_f32 v[4:5], v[4:5], s[50:51], v[82:83] op_sel_hi:[1,0,0] neg_lo:[1,0,0] neg_hi:[1,0,0]
	v_exp_f32_e32 v6, v6
	v_exp_f32_e32 v7, v7
	v_exp_f32_e32 v4, v4
	v_exp_f32_e32 v5, v5
	v_pk_fma_f32 v[2:3], v[2:3], s[50:51], v[86:87] op_sel_hi:[1,0,0] neg_lo:[1,0,0] neg_hi:[1,0,0]
	v_pk_add_f32 v[6:7], v[6:7], 1.0 op_sel_hi:[1,0]
	v_exp_f32_e32 v2, v2
	v_rcp_f32_e32 v6, v6
	v_rcp_f32_e32 v7, v7
	v_pk_add_f32 v[4:5], v[4:5], 1.0 op_sel_hi:[1,0]
	v_exp_f32_e32 v3, v3
	v_rcp_f32_e32 v4, v4
	v_pk_mul_f32 v[6:7], v[92:93], v[6:7] op_sel_hi:[0,1]
	v_exp_f32_e32 v6, v6
	v_exp_f32_e32 v7, v7
	v_rcp_f32_e32 v5, v5
	v_pk_add_f32 v[2:3], v[2:3], 1.0 op_sel_hi:[1,0]
	v_pk_fma_f32 v[0:1], v[0:1], s[50:51], v[86:87] op_sel_hi:[1,0,0] neg_lo:[1,0,0] neg_hi:[1,0,0]
	v_pk_fma_f32 v[8:9], v[6:7], v[6:7], 1.0 op_sel_hi:[1,1,0] neg_lo:[1,0,0] neg_hi:[1,0,0]
	v_rcp_f32_e32 v2, v2
	v_rcp_f32_e32 v3, v3
	v_sqrt_f32_e32 v8, v8
	v_sqrt_f32_e32 v9, v9
	v_pk_mul_f32 v[4:5], v[92:93], v[4:5] op_sel_hi:[0,1]
	v_exp_f32_e32 v150, v4
	v_exp_f32_e32 v0, v0
	v_exp_f32_e32 v1, v1
	v_exp_f32_e32 v151, v5
	v_pk_mul_f32 v[2:3], v[2:3], v[8:9]
	ds_read_u16 v8, v68 offset:31008
	ds_read_u16 v9, v97 offset:31280
	v_pk_add_f32 v[0:1], v[0:1], 1.0 op_sel_hi:[1,0]
	v_pk_fma_f32 v[4:5], v[150:151], v[150:151], 1.0 op_sel_hi:[1,1,0] neg_lo:[1,0,0] neg_hi:[1,0,0]
	ds_read_u16 v10, v97 offset:30736
	ds_read_u16 v11, v68 offset:30464
	v_rcp_f32_e32 v0, v0
	v_rcp_f32_e32 v1, v1
	v_sqrt_f32_e32 v4, v4
	v_sqrt_f32_e32 v5, v5
	s_waitcnt lgkmcnt(3)
	v_lshlrev_b32_e32 v8, 16, v8
	s_waitcnt lgkmcnt(2)
	v_lshlrev_b32_e32 v9, 16, v9
	v_pk_mul_f32 v[154:155], v[2:3], v[8:9]
	v_pk_mul_f32 v[0:1], v[0:1], v[4:5]
	s_waitcnt lgkmcnt(0)
	v_lshlrev_b32_e32 v2, 16, v11
	v_lshlrev_b32_e32 v3, 16, v10
	v_pk_mul_f32 v[152:153], v[0:1], v[2:3]
	s_nop 0
	v_fma_f32 v152, 0, v150, v152
	v_fmac_f32_e32 v153, v151, v152
	v_mul_f32_e32 v151, v150, v151
	v_fma_f32 v156, v6, v153, v154
	v_mul_f32_e32 v158, v6, v151
	v_fmac_f32_e32 v155, v7, v156
	v_mul_f32_e32 v154, v7, v158
	ds_write_b64 v61, v[154:155] offset:3584
	s_waitcnt lgkmcnt(0)
; DI void lru_tile(const Params& p, unsigned char* shm, int c, int nb, const LruPar par) {
;     ...
;         asm volatile("s_waitcnt lgkmcnt(0)" ::: "memory");
;         float carry[8], pref[8]; float cin = 0.f, pa = 1.f;
; #pragma unroll
;         for (int gi = 0; gi < 32; ++gi) {
;             const int G = d == 0 ? gi : 31 - gi; const int rt = G >> 2, qq = G & 3;
;             const f32x2 ah = AG[G * 16 + col];
;             if (qq == q) { carry[rt] = cin; pref[rt] = pa; }
;             cin = fmaf(ah[0], cin, ah[1]); pa *= ah[0];
;         }
;         if (q == 0) AGG[((size_t)d * 128 + c) * 2048 + chg] = (f32x2){pa, cin};
	ds_read2_b64 v[0:3], v59 offset1:16
	v_cndmask_b32_e64 v4, v180, 1.0, s[10:11]
	v_cmp_eq_u32_e64 s[4:5], 1, v99
	v_cmp_eq_u32_e64 s[6:7], 2, v99
	v_cmp_eq_u32_e64 s[8:9], 3, v99
	s_waitcnt lgkmcnt(0)
	v_cndmask_b32_e64 v8, v4, v0, s[4:5]
	ds_read2_b64 v[4:7], v59 offset0:32 offset1:48
	v_fma_f32 v119, 0, v0, v1
	v_cndmask_b32_e64 v9, 1.0, v0, s[4:5]
	v_fma_f32 v127, v2, v119, v3
	v_pk_mul_f32 v[0:1], v[0:1], v[2:3]
	s_waitcnt lgkmcnt(0)
	v_fma_f32 v129, v4, v127, v5
	v_cndmask_b32_e64 v2, v8, v0, s[6:7]
	v_pk_mul_f32 v[4:5], v[0:1], v[4:5]
	v_cndmask_b32_e64 v8, v9, v0, s[6:7]
	v_cndmask_b32_e64 v178, v2, v4, s[8:9]
	ds_read2_b64 v[0:3], v59 offset0:64 offset1:80
	v_cndmask_b32_e64 v181, v8, v4, s[8:9]
	v_fma_f32 v137, v6, v129, v7
	v_pk_mul_f32 v[4:5], v[4:5], v[6:7]
	s_waitcnt lgkmcnt(0)
	v_fma_f32 v139, v0, v137, v1
	v_cndmask_b32_e64 v8, v162, v4, s[10:11]
	v_pk_mul_f32 v[0:1], v[4:5], v[0:1]
	ds_read2_b64 v[4:7], v59 offset0:96 offset1:112
	v_cndmask_b32_e64 v8, v8, v0, s[4:5]
	v_fma_f32 v147, v2, v139, v3
	v_pk_mul_f32 v[0:1], v[0:1], v[2:3]
	ds_read_b64 v[162:163], v59 offset:3840
	v_cndmask_b32_e64 v8, v8, v0, s[6:7]
	s_waitcnt lgkmcnt(1)
	v_fma_f32 v149, v4, v147, v5
	v_pk_mul_f32 v[4:5], v[0:1], v[4:5]
	ds_read2_b64 v[0:3], v59 offset0:128 offset1:144
	v_cndmask_b32_e64 v99, v8, v4, s[8:9]
	v_fma_f32 v157, v6, v149, v7
	v_pk_mul_f32 v[4:5], v[4:5], v[6:7]
	s_waitcnt lgkmcnt(0)
	v_fma_f32 v159, v0, v157, v1
	v_cndmask_b32_e64 v8, v91, v4, s[10:11]
	v_pk_mul_f32 v[0:1], v[4:5], v[0:1]
	ds_read2_b64 v[4:7], v59 offset0:160 offset1:176
	v_cndmask_b32_e64 v8, v8, v0, s[4:5]
	v_fma_f32 v183, v2, v159, v3
	v_pk_mul_f32 v[0:1], v[0:1], v[2:3]
	s_waitcnt lgkmcnt(0)
	v_fma_f32 v184, v4, v183, v5
	v_cndmask_b32_e64 v8, v8, v0, s[6:7]
	v_pk_mul_f32 v[4:5], v[0:1], v[4:5]
	ds_read2_b64 v[0:3], v59 offset0:192 offset1:208
	v_cndmask_b32_e64 v107, v8, v4, s[8:9]
	v_fma_f32 v185, v6, v184, v7
	v_pk_mul_f32 v[4:5], v[4:5], v[6:7]
	s_waitcnt lgkmcnt(0)
	v_fma_f32 v186, v0, v185, v1
	v_cndmask_b32_e64 v8, v89, v4, s[10:11]
	v_pk_mul_f32 v[0:1], v[4:5], v[0:1]
	ds_read2_b64 v[4:7], v59 offset0:224 offset1:240
	v_cndmask_b32_e64 v8, v8, v0, s[4:5]
	v_fma_f32 v187, v2, v186, v3
	v_pk_mul_f32 v[0:1], v[0:1], v[2:3]
	v_add_u32_e32 v89, 0x800, v59
	v_cndmask_b32_e64 v8, v8, v0, s[6:7]
	s_waitcnt lgkmcnt(0)
	v_fma_f32 v188, v4, v187, v5
	v_pk_mul_f32 v[4:5], v[0:1], v[4:5]
	ds_read2_b64 v[0:3], v89 offset1:16
	v_cndmask_b32_e64 v109, v8, v4, s[8:9]
	v_fma_f32 v189, v6, v188, v7
	v_pk_mul_f32 v[4:5], v[4:5], v[6:7]
	s_waitcnt lgkmcnt(0)
	v_fma_f32 v190, v0, v189, v1
	v_cndmask_b32_e64 v8, v85, v4, s[10:11]
	v_pk_mul_f32 v[0:1], v[4:5], v[0:1]
	ds_read2_b64 v[4:7], v89 offset0:32 offset1:48
	v_cndmask_b32_e64 v8, v8, v0, s[4:5]
	v_fma_f32 v192, v2, v190, v3
	v_pk_mul_f32 v[0:1], v[0:1], v[2:3]
	s_waitcnt lgkmcnt(0)
	v_fma_f32 v193, v4, v192, v5
	v_cndmask_b32_e64 v8, v8, v0, s[6:7]
	v_pk_mul_f32 v[4:5], v[0:1], v[4:5]
	ds_read2_b64 v[0:3], v89 offset0:64 offset1:80
	v_cndmask_b32_e64 v117, v8, v4, s[8:9]
	v_fma_f32 v194, v6, v193, v7
	v_pk_mul_f32 v[4:5], v[4:5], v[6:7]
	s_waitcnt lgkmcnt(0)
	v_fma_f32 v195, v0, v194, v1
	v_cndmask_b32_e64 v8, v81, v4, s[10:11]
	v_pk_mul_f32 v[0:1], v[4:5], v[0:1]
	ds_read2_b64 v[4:7], v89 offset0:96 offset1:112
	v_cndmask_b32_e64 v8, v8, v0, s[4:5]
	v_fma_f32 v196, v2, v195, v3
	v_pk_mul_f32 v[0:1], v[0:1], v[2:3]
	s_waitcnt lgkmcnt(0)
	v_fma_f32 v197, v4, v196, v5
	v_cndmask_b32_e64 v8, v8, v0, s[6:7]
	v_pk_mul_f32 v[4:5], v[0:1], v[4:5]
	ds_read2_b64 v[0:3], v89 offset0:128 offset1:144
	v_cndmask_b32_e64 v182, v8, v4, s[8:9]
	v_fma_f32 v198, v6, v197, v7
	v_pk_mul_f32 v[4:5], v[4:5], v[6:7]
	s_waitcnt lgkmcnt(0)
	v_fma_f32 v200, v0, v198, v1
	v_cndmask_b32_e64 v8, v79, v4, s[10:11]
	v_pk_mul_f32 v[0:1], v[4:5], v[0:1]
	ds_read2_b64 v[4:7], v89 offset0:160 offset1:176
	v_cndmask_b32_e64 v8, v8, v0, s[4:5]
	v_fma_f32 v201, v2, v200, v3
	v_pk_mul_f32 v[0:1], v[0:1], v[2:3]
	s_waitcnt lgkmcnt(0)
	v_fma_f32 v204, v4, v201, v5
	v_cndmask_b32_e64 v8, v8, v0, s[6:7]
	v_pk_mul_f32 v[4:5], v[0:1], v[4:5]
	ds_read2_b64 v[0:3], v89 offset0:192 offset1:208
	v_cndmask_b32_e64 v191, v8, v4, s[8:9]
	v_fma_f32 v205, v6, v204, v7
	v_pk_mul_f32 v[4:5], v[4:5], v[6:7]
	s_waitcnt lgkmcnt(0)
	v_fma_f32 v206, v0, v205, v1
	v_cndmask_b32_e64 v6, v77, v4, s[10:11]
	v_pk_mul_f32 v[0:1], v[4:5], v[0:1]
	v_fma_f32 v207, v2, v206, v3
	v_cndmask_b32_e64 v4, v6, v0, s[4:5]
	v_pk_mul_f32 v[0:1], v[0:1], v[2:3]
	s_nop 0
	v_cndmask_b32_e64 v77, v4, v0, s[6:7]
	v_pk_mul_f32 v[0:1], v[0:1], v[162:163]
	v_fmac_f32_e32 v163, v162, v207
	v_cndmask_b32_e64 v199, v77, v0, s[8:9]
	s_and_saveexec_b64 s[60:61], s[10:11]
	s_cbranch_execz .LBB0_230
	ds_read_b64 v[2:3], v59 offset:3968
	v_mov_b32_e32 v181, v178
	s_waitcnt lgkmcnt(0)
	v_pk_mul_f32 v[0:1], v[0:1], v[2:3]
	v_fmac_f32_e32 v3, v2, v163
	v_mov_b32_e32 v1, v3
	global_store_dwordx2 v[56:57], v[0:1], off
